# out-proj/down-proj: gate vectors loaded before the unit's K-loop instead of at the epilogue start behind vmcnt(0)
# baseline (speedup 1.0000x reference)
; #define PG8_STAGE(bufoff, gbase, voff) do { _Pragma("unroll") for (int _i = 0; _i < 2; ++_i) \
;         __builtin_amdgcn_global_load_lds((const unsigned*)((const char*)(gbase) + (voff)[_i]), (LAS unsigned*)(lds + (bufoff) + ldsw + _i * 8192), 16, 0, 0); } while (0)
; #define PG8_LDA(dst, b, h) do { _Pragma("unroll") for (int m = 0; m < 4; ++m) _Pragma("unroll") for (int k = 0; k < 2; ++k) dst[m][k] = *(const LAS bf16x8*)(lds + PG8_SA(b, h) + aoff + m * 2048 + k * 1024); } while (0)
; #define PG8_LDB(dst, b, h) do { _Pragma("unroll") for (int n = 0; n < 2; ++n) _Pragma("unroll") for (int k = 0; k < 2; ++k) dst[n][k] = *(const LAS bf16x8*)(lds + PG8_SB(b, h) + boff + n * 2048 + k * 1024); } while (0)
; #define PG8_WAIT_L(n) asm volatile("s_waitcnt lgkmcnt(" #n ")" ::: "memory")
; #define PG8_BAR __builtin_amdgcn_s_barrier()
; #define PG8_SCHED __builtin_amdgcn_sched_barrier(0)
; template <class Epi>
; __device__ __forceinline__ void gemm_phase(LAS unsigned char* lds, const Gemm g, const StaticOrder& S, const Epi& E, int wv) {
;     ...
;         const bool has_next = S.next(ui + 1, nxt);
;         const char* nA = has_next ? (const char*)g.A + (size_t)nxt.pm * tstepA : cA; const char* nB = has_next ? (const char*)g.Bt + (size_t)nxt.pn * tstepB : cB;
;         for (int t = 0; t < nt; t += 2) {
;             const bool last = (t == nt - 2);
;             const char* a1 = cA + (size_t)(t + 1) * kstep;
;             const char* a2 = last ? nA : cA + (size_t)(t + 2) * kstep; const char* b2 = last ? nB : cB + (size_t)(t + 2) * kstep;
;             const char* a3 = a2 + kstep; const char* b3 = b2 + kstep;
;             PG8_LDB(B0, 0, 0); PG8_SCHED; PG8_LDA(At, 0, 0); PG8_STAGE(PG8_SA(1, 1), a1 + hstep, voffA);
;             PG8_WAIT_L(8); PG8_BAR; PG8_WAIT_L(0); PG8_MMA(0, 0, At, B0); PG8_BAR; PG8_SCHED;
;     __device__ __forceinline__ void operator()(const f32x4 (&acc)[2][2][4][2], const Unit& u, int wr, int wc, int fr, int fq) const {
;         const float* gate = (u.pm >= 64) ? gate1 : gate0;
;         f32x4 gv[2][2];
; #pragma unroll
;         for (int bj = 0; bj < 2; ++bj)
; #pragma unroll
;             for (int n = 0; n < 2; ++n) gv[bj][n] = *(const f32x4*)(gate + u.pn * 256 + bj * 128 + wc * 32 + n * 16 + 4 * fq);
.LBB0_845:
	s_ashr_i32 s37, s36, 31
	v_cmp_lt_i64_e32 vcc, s[38:39], v[158:159]
	s_lshl_b64 s[38:39], s[36:37], 19
	s_add_u32 s38, s54, s38
	s_addc_u32 s39, s55, s39
	s_and_b64 s[40:41], vcc, exec
	s_cselect_b32 s37, s39, s45
	s_cselect_b32 s43, s38, s44
	s_ashr_i32 s35, s34, 31
	s_lshl_b64 s[40:41], s[34:35], 19
	s_add_u32 s40, s56, s40
	s_addc_u32 s41, s57, s41
	s_and_b64 s[48:49], vcc, exec
	s_cselect_b32 s35, s41, s47
	s_cselect_b32 s79, s40, s46
	s_add_u32 s80, s46, 0x100
	s_addc_u32 s81, s47, 0
	s_mov_b32 s82, -2
	s_cmp_gt_i32 s42, 63
	s_cselect_b32 s98, s74, 0x1642000
	s_add_u32 s98, s6, s98
	s_addc_u32 s99, s7, 0
	s_lshl_b32 s100, s8, 8
	s_ashr_i32 s101, s100, 31
	s_lshl_b64 s[100:101], s[100:101], 2
	s_add_u32 s98, s98, s100
	s_addc_u32 s99, s99, s101
	s_lshl_b32 s100, s66, 2
	s_add_u32 s98, s98, s100
	s_addc_u32 s99, s99, 0
	v_mbcnt_lo_u32_b32 v240, -1, 0
	v_mbcnt_hi_u32_b32 v240, -1, v240
	v_lshrrev_b32_e32 v240, 2, v240
	v_and_b32_e32 v240, 28, v240
	v_lshlrev_b32_e32 v240, 2, v240
	global_load_dwordx4 v[236:239], v240, s[98:99]
	global_load_dwordx4 v[232:235], v240, s[98:99] offset:64
	global_load_dwordx4 v[228:231], v240, s[98:99] offset:512
	global_load_dwordx4 v[224:227], v240, s[98:99] offset:576
	ds_read_b128 v[128:131], v165
	ds_read_b128 v[132:135], v165 offset:1024
	ds_read_b128 v[136:139], v165 offset:2048
	ds_read_b128 v[140:143], v165 offset:3072
	s_add_u32 s46, s44, 0x100
	s_addc_u32 s47, s45, 0
	s_cmp_eq_u32 s82, 12
	s_cselect_b32 s51, s37, s47
	s_cselect_b32 s50, s43, s46
	s_cselect_b32 s49, s35, s81
	s_cselect_b32 s48, s79, s80
	ds_read_b128 v[168:171], v166
	ds_read_b128 v[172:175], v166 offset:1024
	ds_read_b128 v[176:179], v166 offset:2048
	ds_read_b128 v[180:183], v166 offset:3072
	ds_read_b128 v[184:187], v166 offset:4096
	ds_read_b128 v[188:191], v166 offset:5120
	ds_read_b128 v[192:195], v166 offset:6144
	ds_read_b128 v[196:199], v166 offset:7168
	ds_read_b128 v[200:203], v167
	ds_read_b128 v[204:207], v167 offset:1024
	ds_read_b128 v[208:211], v167 offset:2048
	ds_read_b128 v[212:215], v167 offset:3072
	v_lshl_add_u64 v[252:253], s[44:45], 0, v[154:155]
	s_add_i32 m0, s59, 0xc000
	s_nop 0
	global_load_lds_dwordx4 v[252:253], off
	v_lshl_add_u64 v[252:253], s[44:45], 0, v[156:157]
	s_add_i32 m0, s59, 0xe000
	s_nop 0
	global_load_lds_dwordx4 v[252:253], off
	s_waitcnt vmcnt(8)
	s_waitcnt lgkmcnt(0)
	s_barrier
	s_setprio 1
	v_mfma_f32_16x16x32_bf16 v[124:127], v[128:131], v[168:171], 0
	v_mfma_f32_16x16x32_bf16 v[120:123], v[136:139], v[168:171], 0
	v_mfma_f32_16x16x32_bf16 v[116:119], v[128:131], v[176:179], 0
	v_mfma_f32_16x16x32_bf16 v[112:115], v[136:139], v[176:179], 0
	v_mfma_f32_16x16x32_bf16 v[108:111], v[128:131], v[184:187], 0
	v_mfma_f32_16x16x32_bf16 v[96:99], v[136:139], v[184:187], 0
	v_mfma_f32_16x16x32_bf16 v[80:83], v[128:131], v[192:195], 0
	v_mfma_f32_16x16x32_bf16 v[72:75], v[136:139], v[192:195], 0
	v_mfma_f32_16x16x32_bf16 v[124:127], v[132:135], v[172:175], v[124:127]
	v_mfma_f32_16x16x32_bf16 v[120:123], v[140:143], v[172:175], v[120:123]
	v_mfma_f32_16x16x32_bf16 v[116:119], v[132:135], v[180:183], v[116:119]
	v_mfma_f32_16x16x32_bf16 v[112:115], v[140:143], v[180:183], v[112:115]
	v_mfma_f32_16x16x32_bf16 v[108:111], v[132:135], v[188:191], v[108:111]
	v_mfma_f32_16x16x32_bf16 v[96:99], v[140:143], v[188:191], v[96:99]
	v_mfma_f32_16x16x32_bf16 v[80:83], v[132:135], v[196:199], v[80:83]
	v_mfma_f32_16x16x32_bf16 v[72:75], v[140:143], v[196:199], v[72:75]
	v_mfma_f32_16x16x32_bf16 v[104:107], v[200:203], v[168:171], 0
	v_mfma_f32_16x16x32_bf16 v[100:103], v[208:211], v[168:171], 0
	v_mfma_f32_16x16x32_bf16 v[92:95], v[200:203], v[176:179], 0
	v_mfma_f32_16x16x32_bf16 v[88:91], v[208:211], v[176:179], 0
	v_mfma_f32_16x16x32_bf16 v[84:87], v[200:203], v[184:187], 0
	v_mfma_f32_16x16x32_bf16 v[76:79], v[208:211], v[184:187], 0
	v_mfma_f32_16x16x32_bf16 v[68:71], v[200:203], v[192:195], 0
	v_mfma_f32_16x16x32_bf16 v[64:67], v[208:211], v[192:195], 0
	v_mfma_f32_16x16x32_bf16 v[104:107], v[204:207], v[172:175], v[104:107]
	v_mfma_f32_16x16x32_bf16 v[100:103], v[212:215], v[172:175], v[100:103]
	v_mfma_f32_16x16x32_bf16 v[92:95], v[204:207], v[180:183], v[92:95]
	v_mfma_f32_16x16x32_bf16 v[88:91], v[212:215], v[180:183], v[88:91]
	v_mfma_f32_16x16x32_bf16 v[84:87], v[204:207], v[188:191], v[84:87]
	v_mfma_f32_16x16x32_bf16 v[76:79], v[212:215], v[188:191], v[76:79]
	v_mfma_f32_16x16x32_bf16 v[68:71], v[204:207], v[196:199], v[68:71]
	v_mfma_f32_16x16x32_bf16 v[64:67], v[212:215], v[196:199], v[64:67]
	s_setprio 0
	s_barrier
	ds_read_b128 v[168:171], v166 offset:16384
	ds_read_b128 v[172:175], v166 offset:17408
	ds_read_b128 v[176:179], v166 offset:18432
	ds_read_b128 v[180:183], v166 offset:19456
	ds_read_b128 v[184:187], v166 offset:20480
	ds_read_b128 v[188:191], v166 offset:21504
	ds_read_b128 v[192:195], v166 offset:22528
	ds_read_b128 v[196:199], v166 offset:23552
	s_add_i32 s44, s72, s58
	v_lshl_add_u64 v[162:163], s[48:49], 0, v[146:147]
	s_mov_b32 m0, s44
	s_nop 0
	global_load_lds_dwordx4 v[162:163], off
	v_lshl_add_u64 v[216:217], s[48:49], 0, v[150:151]
	s_add_i32 m0, s44, 0x2000
	s_nop 0
	global_load_lds_dwordx4 v[216:217], off
	s_mov_b32 m0, s59
	v_lshl_add_u64 v[218:219], s[50:51], 0, v[144:145]
	global_load_lds_dwordx4 v[218:219], off
	v_lshl_add_u64 v[220:221], s[50:51], 0, v[148:149]
	s_mov_b32 m0, s60
	s_nop 0
	global_load_lds_dwordx4 v[220:221], off
	s_add_u32 s44, s48, 0x40000
	s_addc_u32 s45, s49, 0
	s_add_i32 s83, s73, s58
	v_lshl_add_u64 v[254:255], s[44:45], 0, v[146:147]
	s_mov_b32 m0, s83
	s_nop 0
	global_load_lds_dwordx4 v[254:255], off
	v_lshl_add_u64 v[254:255], s[44:45], 0, v[150:151]
	s_add_i32 m0, s83, 0x2000
	s_nop 0
	global_load_lds_dwordx4 v[254:255], off
	s_waitcnt vmcnt(8)
	s_waitcnt lgkmcnt(0)
	s_barrier
; #define PG8_STAGE(bufoff, gbase, voff) do { _Pragma("unroll") for (int _i = 0; _i < 2; ++_i) \
;         __builtin_amdgcn_global_load_lds((const unsigned*)((const char*)(gbase) + (voff)[_i]), (LAS unsigned*)(lds + (bufoff) + ldsw + _i * 8192), 16, 0, 0); } while (0)
; #define PG8_LDA(dst, b, h) do { _Pragma("unroll") for (int m = 0; m < 4; ++m) _Pragma("unroll") for (int k = 0; k < 2; ++k) dst[m][k] = *(const LAS bf16x8*)(lds + PG8_SA(b, h) + aoff + m * 2048 + k * 1024); } while (0)
; #define PG8_LDB(dst, b, h) do { _Pragma("unroll") for (int n = 0; n < 2; ++n) _Pragma("unroll") for (int k = 0; k < 2; ++k) dst[n][k] = *(const LAS bf16x8*)(lds + PG8_SB(b, h) + boff + n * 2048 + k * 1024); } while (0)
; #define PG8_WAIT_V(n) asm volatile("s_waitcnt vmcnt(" #n ")" ::: "memory")
; #define PG8_WAIT_L(n) asm volatile("s_waitcnt lgkmcnt(" #n ")" ::: "memory")
; #define PG8_BAR __builtin_amdgcn_s_barrier()
; template <class Epi>
; __device__ __forceinline__ void gemm_phase(LAS unsigned char* lds, const Gemm g, const StaticOrder& S, const Epi& E, int wv) {
;     ...
;         for (int t = 0; t < nt; t += 2) {
;             const bool last = (t == nt - 2);
;             const char* a1 = cA + (size_t)(t + 1) * kstep;
;             const char* a2 = last ? nA : cA + (size_t)(t + 2) * kstep; const char* b2 = last ? nB : cB + (size_t)(t + 2) * kstep;
;             const char* a3 = a2 + kstep; const char* b3 = b2 + kstep;
;             PG8_LDB(B0, 0, 0); PG8_SCHED; PG8_LDA(At, 0, 0); PG8_STAGE(PG8_SA(1, 1), a1 + hstep, voffA);
;             PG8_WAIT_L(8); PG8_BAR; PG8_WAIT_L(0); PG8_MMA(0, 0, At, B0); PG8_BAR; PG8_SCHED;
;             PG8_LDB(B1, 0, 1); PG8_STAGE(PG8_SB(0, 0), b2, voffB);
;             PG8_BAR; PG8_WAIT_L(0); PG8_MMA(0, 1, At, B1); PG8_BAR;
;             PG8_LDA(At, 0, 1); PG8_STAGE(PG8_SA(0, 0), a2, voffA);
;             PG8_BAR; PG8_WAIT_L(0); PG8_MMA(1, 0, At, B0); PG8_BAR; PG8_SCHED;
;             PG8_STAGE(PG8_SB(0, 1), b2 + hstep, voffB);
;             PG8_WAIT_V(6); PG8_BAR; PG8_MMA(1, 1, At, B1); PG8_BAR;
;             PG8_LDB(B0, 1, 0); PG8_SCHED; PG8_LDA(At, 1, 0); PG8_STAGE(PG8_SA(0, 1), a2 + hstep, voffA);
;             PG8_WAIT_L(8); PG8_BAR; PG8_WAIT_L(0); PG8_MMA(0, 0, At, B0); PG8_BAR; PG8_SCHED;
;             PG8_LDB(B1, 1, 1); PG8_STAGE(PG8_SB(1, 0), b3, voffB);
;             PG8_BAR; PG8_WAIT_L(0); PG8_MMA(0, 1, At, B1); PG8_BAR;
	s_setprio 1
	v_mfma_f32_16x16x32_bf16 v[60:63], v[128:131], v[168:171], 0
	v_mfma_f32_16x16x32_bf16 v[56:59], v[136:139], v[168:171], 0
	v_mfma_f32_16x16x32_bf16 v[48:51], v[128:131], v[176:179], 0
	v_mfma_f32_16x16x32_bf16 v[40:43], v[136:139], v[176:179], 0
	v_mfma_f32_16x16x32_bf16 v[32:35], v[128:131], v[184:187], 0
	v_mfma_f32_16x16x32_bf16 v[24:27], v[136:139], v[184:187], 0
	v_mfma_f32_16x16x32_bf16 v[16:19], v[128:131], v[192:195], 0
	v_mfma_f32_16x16x32_bf16 v[8:11], v[136:139], v[192:195], 0
	v_mfma_f32_16x16x32_bf16 v[60:63], v[132:135], v[172:175], v[60:63]
	v_mfma_f32_16x16x32_bf16 v[56:59], v[140:143], v[172:175], v[56:59]
	v_mfma_f32_16x16x32_bf16 v[48:51], v[132:135], v[180:183], v[48:51]
	v_mfma_f32_16x16x32_bf16 v[40:43], v[140:143], v[180:183], v[40:43]
	v_mfma_f32_16x16x32_bf16 v[32:35], v[132:135], v[188:191], v[32:35]
	v_mfma_f32_16x16x32_bf16 v[24:27], v[140:143], v[188:191], v[24:27]
	v_mfma_f32_16x16x32_bf16 v[16:19], v[132:135], v[196:199], v[16:19]
	v_mfma_f32_16x16x32_bf16 v[8:11], v[140:143], v[196:199], v[8:11]
	v_mfma_f32_16x16x32_bf16 v[52:55], v[200:203], v[168:171], 0
	v_mfma_f32_16x16x32_bf16 v[44:47], v[208:211], v[168:171], 0
	v_mfma_f32_16x16x32_bf16 v[36:39], v[200:203], v[176:179], 0
	v_mfma_f32_16x16x32_bf16 v[28:31], v[208:211], v[176:179], 0
	v_mfma_f32_16x16x32_bf16 v[20:23], v[200:203], v[184:187], 0
	v_mfma_f32_16x16x32_bf16 v[12:15], v[208:211], v[184:187], 0
	v_mfma_f32_16x16x32_bf16 v[4:7], v[200:203], v[192:195], 0
	v_mfma_f32_16x16x32_bf16 v[0:3], v[208:211], v[192:195], 0
	v_mfma_f32_16x16x32_bf16 v[52:55], v[204:207], v[172:175], v[52:55]
	v_mfma_f32_16x16x32_bf16 v[44:47], v[212:215], v[172:175], v[44:47]
	v_mfma_f32_16x16x32_bf16 v[36:39], v[204:207], v[180:183], v[36:39]
	v_mfma_f32_16x16x32_bf16 v[28:31], v[212:215], v[180:183], v[28:31]
	v_mfma_f32_16x16x32_bf16 v[20:23], v[204:207], v[188:191], v[20:23]
	v_mfma_f32_16x16x32_bf16 v[12:15], v[212:215], v[188:191], v[12:15]
	v_mfma_f32_16x16x32_bf16 v[4:7], v[204:207], v[196:199], v[4:7]
	v_mfma_f32_16x16x32_bf16 v[0:3], v[212:215], v[196:199], v[0:3]
	s_setprio 0
	s_add_i32 s83, 0, 0x18000
	v_add_u32_e32 v140, s83, v164
	s_barrier
	ds_read_b128 v[128:131], v140
	ds_read_b128 v[132:135], v140 offset:1024
	ds_read_b128 v[136:139], v140 offset:2048
	ds_read_b128 v[140:143], v140 offset:3072
	s_add_u32 s44, s50, 0x40000
	s_addc_u32 s45, s51, 0
	ds_read_b128 v[168:171], v166 offset:32768
	ds_read_b128 v[172:175], v166 offset:33792
	ds_read_b128 v[176:179], v166 offset:34816
	ds_read_b128 v[180:183], v166 offset:35840
	ds_read_b128 v[184:187], v166 offset:36864
	ds_read_b128 v[188:191], v166 offset:37888
	ds_read_b128 v[192:195], v166 offset:38912
	ds_read_b128 v[196:199], v166 offset:39936
	s_mov_b32 m0, s61
	v_lshl_add_u64 v[252:253], s[44:45], 0, v[144:145]
	global_load_lds_dwordx4 v[252:253], off
	v_lshl_add_u64 v[252:253], s[44:45], 0, v[148:149]
	s_mov_b32 m0, s64
	s_nop 0
	global_load_lds_dwordx4 v[252:253], off
	s_add_i32 s50, 0, 0x1c000
	v_add_u32_e32 v152, s50, v164
	ds_read_b128 v[200:203], v152
	ds_read_b128 v[204:207], v152 offset:1024
	ds_read_b128 v[208:211], v152 offset:2048
	ds_read_b128 v[212:215], v152 offset:3072
	s_waitcnt vmcnt(8)
	s_waitcnt lgkmcnt(0)
	s_barrier
	s_setprio 1
	v_mfma_f32_16x16x32_bf16 v[124:127], v[128:131], v[168:171], v[124:127]
	v_mfma_f32_16x16x32_bf16 v[120:123], v[136:139], v[168:171], v[120:123]
	v_mfma_f32_16x16x32_bf16 v[116:119], v[128:131], v[176:179], v[116:119]
	v_mfma_f32_16x16x32_bf16 v[112:115], v[136:139], v[176:179], v[112:115]
	v_mfma_f32_16x16x32_bf16 v[108:111], v[128:131], v[184:187], v[108:111]
	v_mfma_f32_16x16x32_bf16 v[96:99], v[136:139], v[184:187], v[96:99]
	v_mfma_f32_16x16x32_bf16 v[80:83], v[128:131], v[192:195], v[80:83]
	v_mfma_f32_16x16x32_bf16 v[72:75], v[136:139], v[192:195], v[72:75]
	v_mfma_f32_16x16x32_bf16 v[124:127], v[132:135], v[172:175], v[124:127]
	v_mfma_f32_16x16x32_bf16 v[120:123], v[140:143], v[172:175], v[120:123]
	v_mfma_f32_16x16x32_bf16 v[116:119], v[132:135], v[180:183], v[116:119]
	v_mfma_f32_16x16x32_bf16 v[112:115], v[140:143], v[180:183], v[112:115]
	v_mfma_f32_16x16x32_bf16 v[108:111], v[132:135], v[188:191], v[108:111]
	v_mfma_f32_16x16x32_bf16 v[96:99], v[140:143], v[188:191], v[96:99]
	v_mfma_f32_16x16x32_bf16 v[80:83], v[132:135], v[196:199], v[80:83]
	v_mfma_f32_16x16x32_bf16 v[72:75], v[140:143], v[196:199], v[72:75]
	v_mfma_f32_16x16x32_bf16 v[104:107], v[200:203], v[168:171], v[104:107]
	v_mfma_f32_16x16x32_bf16 v[100:103], v[208:211], v[168:171], v[100:103]
	v_mfma_f32_16x16x32_bf16 v[92:95], v[200:203], v[176:179], v[92:95]
	v_mfma_f32_16x16x32_bf16 v[88:91], v[208:211], v[176:179], v[88:91]
	v_mfma_f32_16x16x32_bf16 v[84:87], v[200:203], v[184:187], v[84:87]
	v_mfma_f32_16x16x32_bf16 v[76:79], v[208:211], v[184:187], v[76:79]
	v_mfma_f32_16x16x32_bf16 v[68:71], v[200:203], v[192:195], v[68:71]
	v_mfma_f32_16x16x32_bf16 v[64:67], v[208:211], v[192:195], v[64:67]
	v_mfma_f32_16x16x32_bf16 v[104:107], v[204:207], v[172:175], v[104:107]
	v_mfma_f32_16x16x32_bf16 v[100:103], v[212:215], v[172:175], v[100:103]
	v_mfma_f32_16x16x32_bf16 v[92:95], v[204:207], v[180:183], v[92:95]
	v_mfma_f32_16x16x32_bf16 v[88:91], v[212:215], v[180:183], v[88:91]
	v_mfma_f32_16x16x32_bf16 v[84:87], v[204:207], v[188:191], v[84:87]
	v_mfma_f32_16x16x32_bf16 v[76:79], v[212:215], v[188:191], v[76:79]
	v_mfma_f32_16x16x32_bf16 v[68:71], v[204:207], v[196:199], v[68:71]
	v_mfma_f32_16x16x32_bf16 v[64:67], v[212:215], v[196:199], v[64:67]
	s_setprio 0
	s_barrier
; #define PG8_STAGE(bufoff, gbase, voff) do { _Pragma("unroll") for (int _i = 0; _i < 2; ++_i) \
;         __builtin_amdgcn_global_load_lds((const unsigned*)((const char*)(gbase) + (voff)[_i]), (LAS unsigned*)(lds + (bufoff) + ldsw + _i * 8192), 16, 0, 0); } while (0)
; #define PG8_LDA(dst, b, h) do { _Pragma("unroll") for (int m = 0; m < 4; ++m) _Pragma("unroll") for (int k = 0; k < 2; ++k) dst[m][k] = *(const LAS bf16x8*)(lds + PG8_SA(b, h) + aoff + m * 2048 + k * 1024); } while (0)
; #define PG8_LDB(dst, b, h) do { _Pragma("unroll") for (int n = 0; n < 2; ++n) _Pragma("unroll") for (int k = 0; k < 2; ++k) dst[n][k] = *(const LAS bf16x8*)(lds + PG8_SB(b, h) + boff + n * 2048 + k * 1024); } while (0)
; #define PG8_MMA(ai, bj, At, Bt) do { __builtin_amdgcn_s_setprio(1); _Pragma("unroll") for (int m = 0; m < 4; ++m) _Pragma("unroll") for (int n = 0; n < 2; ++n) _Pragma("unroll") for (int k = 0; k < 2; ++k) \
;         acc[ai][bj][m][n] = __builtin_amdgcn_mfma_f32_16x16x32_bf16(Bt[n][k], At[m][k], acc[ai][bj][m][n], 0, 0, 0); __builtin_amdgcn_s_setprio(0); } while (0)
; #define PG8_WAIT_V(n) asm volatile("s_waitcnt vmcnt(" #n ")" ::: "memory")
; #define PG8_WAIT_L(n) asm volatile("s_waitcnt lgkmcnt(" #n ")" ::: "memory")
; #define PG8_BAR __builtin_amdgcn_s_barrier()
; #define PG8_SCHED __builtin_amdgcn_sched_barrier(0)
; template <class Epi>
; __device__ __forceinline__ void gemm_phase(LAS unsigned char* lds, const Gemm g, const StaticOrder& S, const Epi& E, int wv) {
;     ...
;             PG8_LDB(B0, 0, 0); PG8_SCHED; PG8_LDA(At, 0, 0); PG8_STAGE(PG8_SA(1, 1), a1 + hstep, voffA);
;             PG8_WAIT_L(8); PG8_BAR; PG8_WAIT_L(0); PG8_MMA(0, 0, At, B0); PG8_BAR; PG8_SCHED;
;     ...
;             PG8_WAIT_V(6); PG8_BAR; PG8_MMA(1, 1, At, B1); PG8_BAR;
;             PG8_LDB(B0, 1, 0); PG8_SCHED; PG8_LDA(At, 1, 0); PG8_STAGE(PG8_SA(0, 1), a2 + hstep, voffA);
;             PG8_WAIT_L(8); PG8_BAR; PG8_WAIT_L(0); PG8_MMA(0, 0, At, B0); PG8_BAR; PG8_SCHED;
;             PG8_LDB(B1, 1, 1); PG8_STAGE(PG8_SB(1, 0), b3, voffB);
;             PG8_BAR; PG8_WAIT_L(0); PG8_MMA(0, 1, At, B1); PG8_BAR;
;             PG8_LDA(At, 1, 1); PG8_STAGE(PG8_SA(1, 0), a3, voffA);
;             PG8_BAR; PG8_WAIT_L(0); PG8_MMA(1, 0, At, B0); PG8_BAR; PG8_SCHED;
;             PG8_STAGE(PG8_SB(1, 1), b3 + hstep, voffB);
;             PG8_WAIT_V(6); PG8_BAR; PG8_MMA(1, 1, At, B1); PG8_BAR;
	ds_read_b128 v[168:171], v166 offset:49152
	ds_read_b128 v[172:175], v166 offset:50176
	ds_read_b128 v[176:179], v166 offset:51200
	ds_read_b128 v[180:183], v166 offset:52224
	ds_read_b128 v[184:187], v166 offset:53248
	ds_read_b128 v[188:191], v166 offset:54272
	ds_read_b128 v[192:195], v166 offset:55296
	ds_read_b128 v[196:199], v166 offset:56320
	s_add_i32 s44, s83, s58
	v_lshl_add_u64 v[162:163], v[162:163], 0, s[16:17]
	s_mov_b32 m0, s44
	s_nop 0
	global_load_lds_dwordx4 v[162:163], off
	v_lshl_add_u64 v[162:163], v[216:217], 0, s[16:17]
	s_add_i32 m0, s44, 0x2000
	s_nop 0
	global_load_lds_dwordx4 v[162:163], off
	s_mov_b32 m0, s67
	v_lshl_add_u64 v[162:163], v[218:219], 0, s[16:17]
	global_load_lds_dwordx4 v[162:163], off
	v_lshl_add_u64 v[162:163], v[220:221], 0, s[16:17]
	s_mov_b32 m0, s68
	s_nop 0
	global_load_lds_dwordx4 v[162:163], off
	s_add_u32 s44, s48, 0x40080
	s_addc_u32 s45, s49, 0
	s_add_i32 s48, s50, s58
	v_lshl_add_u64 v[254:255], s[44:45], 0, v[146:147]
	s_mov_b32 m0, s48
	s_nop 0
	global_load_lds_dwordx4 v[254:255], off
	v_lshl_add_u64 v[254:255], s[44:45], 0, v[150:151]
	s_add_i32 m0, s48, 0x2000
	s_nop 0
	global_load_lds_dwordx4 v[254:255], off
	s_waitcnt vmcnt(8)
	s_waitcnt lgkmcnt(0)
	s_barrier
	s_setprio 1
	v_mfma_f32_16x16x32_bf16 v[60:63], v[128:131], v[168:171], v[60:63]
	v_mfma_f32_16x16x32_bf16 v[56:59], v[136:139], v[168:171], v[56:59]
	v_mfma_f32_16x16x32_bf16 v[48:51], v[128:131], v[176:179], v[48:51]
	v_mfma_f32_16x16x32_bf16 v[40:43], v[136:139], v[176:179], v[40:43]
	v_mfma_f32_16x16x32_bf16 v[32:35], v[128:131], v[184:187], v[32:35]
	v_mfma_f32_16x16x32_bf16 v[24:27], v[136:139], v[184:187], v[24:27]
	v_mfma_f32_16x16x32_bf16 v[16:19], v[128:131], v[192:195], v[16:19]
	v_mfma_f32_16x16x32_bf16 v[8:11], v[136:139], v[192:195], v[8:11]
	v_mfma_f32_16x16x32_bf16 v[60:63], v[132:135], v[172:175], v[60:63]
	v_mfma_f32_16x16x32_bf16 v[56:59], v[140:143], v[172:175], v[56:59]
	v_mfma_f32_16x16x32_bf16 v[48:51], v[132:135], v[180:183], v[48:51]
	v_mfma_f32_16x16x32_bf16 v[40:43], v[140:143], v[180:183], v[40:43]
	v_mfma_f32_16x16x32_bf16 v[32:35], v[132:135], v[188:191], v[32:35]
	v_mfma_f32_16x16x32_bf16 v[24:27], v[140:143], v[188:191], v[24:27]
	v_mfma_f32_16x16x32_bf16 v[16:19], v[132:135], v[196:199], v[16:19]
	v_mfma_f32_16x16x32_bf16 v[8:11], v[140:143], v[196:199], v[8:11]
	v_mfma_f32_16x16x32_bf16 v[52:55], v[200:203], v[168:171], v[52:55]
	v_mfma_f32_16x16x32_bf16 v[44:47], v[208:211], v[168:171], v[44:47]
	v_mfma_f32_16x16x32_bf16 v[36:39], v[200:203], v[176:179], v[36:39]
	v_mfma_f32_16x16x32_bf16 v[28:31], v[208:211], v[176:179], v[28:31]
	v_mfma_f32_16x16x32_bf16 v[20:23], v[200:203], v[184:187], v[20:23]
	v_mfma_f32_16x16x32_bf16 v[12:15], v[208:211], v[184:187], v[12:15]
	v_mfma_f32_16x16x32_bf16 v[4:7], v[200:203], v[192:195], v[4:7]
	v_mfma_f32_16x16x32_bf16 v[0:3], v[208:211], v[192:195], v[0:3]
	v_mfma_f32_16x16x32_bf16 v[52:55], v[204:207], v[172:175], v[52:55]
	v_mfma_f32_16x16x32_bf16 v[44:47], v[212:215], v[172:175], v[44:47]
	v_mfma_f32_16x16x32_bf16 v[36:39], v[204:207], v[180:183], v[36:39]
	v_mfma_f32_16x16x32_bf16 v[28:31], v[212:215], v[180:183], v[28:31]
	v_mfma_f32_16x16x32_bf16 v[20:23], v[204:207], v[188:191], v[20:23]
	v_mfma_f32_16x16x32_bf16 v[12:15], v[212:215], v[188:191], v[12:15]
	v_mfma_f32_16x16x32_bf16 v[4:7], v[204:207], v[196:199], v[4:7]
	v_mfma_f32_16x16x32_bf16 v[0:3], v[212:215], v[196:199], v[0:3]
	s_setprio 0
	s_add_i32 s82, s82, 2
	s_add_u32 s80, s80, 0x100
	s_addc_u32 s81, s81, 0
	s_cmp_gt_u32 s82, 13
	s_mov_b64 s[44:45], s[46:47]
	s_barrier
.LBB0_846:
	ds_read_b128 v[128:131], v165
	ds_read_b128 v[132:135], v165 offset:1024
	ds_read_b128 v[136:139], v165 offset:2048
	ds_read_b128 v[140:143], v165 offset:3072
	s_add_u32 s46, s44, 0x100
	s_addc_u32 s47, s45, 0
	s_cmp_eq_u32 s82, 12
	s_cselect_b32 s51, s37, s47
	s_cselect_b32 s50, s43, s46
	s_cselect_b32 s49, s35, s81
	s_cselect_b32 s48, s79, s80
	ds_read_b128 v[168:171], v166
	ds_read_b128 v[172:175], v166 offset:1024
	ds_read_b128 v[176:179], v166 offset:2048
	ds_read_b128 v[180:183], v166 offset:3072
	ds_read_b128 v[184:187], v166 offset:4096
	ds_read_b128 v[188:191], v166 offset:5120
	ds_read_b128 v[192:195], v166 offset:6144
	ds_read_b128 v[196:199], v166 offset:7168
	ds_read_b128 v[200:203], v167
	ds_read_b128 v[204:207], v167 offset:1024
	ds_read_b128 v[208:211], v167 offset:2048
	ds_read_b128 v[212:215], v167 offset:3072
	v_lshl_add_u64 v[252:253], s[44:45], 0, v[154:155]
	s_add_i32 m0, s59, 0xc000
	s_nop 0
	global_load_lds_dwordx4 v[252:253], off
	v_lshl_add_u64 v[252:253], s[44:45], 0, v[156:157]
	s_add_i32 m0, s59, 0xe000
	s_nop 0
	global_load_lds_dwordx4 v[252:253], off
	s_waitcnt vmcnt(8)
	s_waitcnt lgkmcnt(0)
	s_barrier
; #define PG8_STAGE(bufoff, gbase, voff) do { _Pragma("unroll") for (int _i = 0; _i < 2; ++_i) \
;         __builtin_amdgcn_global_load_lds((const unsigned*)((const char*)(gbase) + (voff)[_i]), (LAS unsigned*)(lds + (bufoff) + ldsw + _i * 8192), 16, 0, 0); } while (0)
; #define PG8_LDA(dst, b, h) do { _Pragma("unroll") for (int m = 0; m < 4; ++m) _Pragma("unroll") for (int k = 0; k < 2; ++k) dst[m][k] = *(const LAS bf16x8*)(lds + PG8_SA(b, h) + aoff + m * 2048 + k * 1024); } while (0)
; #define PG8_LDB(dst, b, h) do { _Pragma("unroll") for (int n = 0; n < 2; ++n) _Pragma("unroll") for (int k = 0; k < 2; ++k) dst[n][k] = *(const LAS bf16x8*)(lds + PG8_SB(b, h) + boff + n * 2048 + k * 1024); } while (0)
; #define PG8_MMA(ai, bj, At, Bt) do { __builtin_amdgcn_s_setprio(1); _Pragma("unroll") for (int m = 0; m < 4; ++m) _Pragma("unroll") for (int n = 0; n < 2; ++n) _Pragma("unroll") for (int k = 0; k < 2; ++k) \
;         acc[ai][bj][m][n] = __builtin_amdgcn_mfma_f32_16x16x32_bf16(Bt[n][k], At[m][k], acc[ai][bj][m][n], 0, 0, 0); __builtin_amdgcn_s_setprio(0); } while (0)
; #define PG8_BAR __builtin_amdgcn_s_barrier()
; template <class Epi>
; __device__ __forceinline__ void gemm_phase(LAS unsigned char* lds, const Gemm g, const StaticOrder& S, const Epi& E, int wv) {
;     ...
;             PG8_LDB(B0, 0, 0); PG8_SCHED; PG8_LDA(At, 0, 0); PG8_STAGE(PG8_SA(1, 1), a1 + hstep, voffA);
;             PG8_WAIT_L(8); PG8_BAR; PG8_WAIT_L(0); PG8_MMA(0, 0, At, B0); PG8_BAR; PG8_SCHED;
;             PG8_LDB(B1, 0, 1); PG8_STAGE(PG8_SB(0, 0), b2, voffB);
;             PG8_BAR; PG8_WAIT_L(0); PG8_MMA(0, 1, At, B1); PG8_BAR;
;             PG8_LDA(At, 0, 1); PG8_STAGE(PG8_SA(0, 0), a2, voffA);
;             PG8_BAR; PG8_WAIT_L(0); PG8_MMA(1, 0, At, B0); PG8_BAR; PG8_SCHED;
;             PG8_STAGE(PG8_SB(0, 1), b2 + hstep, voffB);
;             PG8_WAIT_V(6); PG8_BAR; PG8_MMA(1, 1, At, B1); PG8_BAR;
;             PG8_LDB(B0, 1, 0); PG8_SCHED; PG8_LDA(At, 1, 0); PG8_STAGE(PG8_SA(0, 1), a2 + hstep, voffA);
;             PG8_WAIT_L(8); PG8_BAR; PG8_WAIT_L(0); PG8_MMA(0, 0, At, B0); PG8_BAR; PG8_SCHED;
;             PG8_LDB(B1, 1, 1); PG8_STAGE(PG8_SB(1, 0), b3, voffB);
;             PG8_BAR; PG8_WAIT_L(0); PG8_MMA(0, 1, At, B1); PG8_BAR;
;             PG8_LDA(At, 1, 1); PG8_STAGE(PG8_SA(1, 0), a3, voffA);
;             PG8_BAR; PG8_WAIT_L(0); PG8_MMA(1, 0, At, B0); PG8_BAR; PG8_SCHED;
	s_setprio 1
	v_mfma_f32_16x16x32_bf16 v[124:127], v[128:131], v[168:171], v[124:127]
	v_mfma_f32_16x16x32_bf16 v[120:123], v[136:139], v[168:171], v[120:123]
	v_mfma_f32_16x16x32_bf16 v[116:119], v[128:131], v[176:179], v[116:119]
	v_mfma_f32_16x16x32_bf16 v[112:115], v[136:139], v[176:179], v[112:115]
	v_mfma_f32_16x16x32_bf16 v[108:111], v[128:131], v[184:187], v[108:111]
	v_mfma_f32_16x16x32_bf16 v[96:99], v[136:139], v[184:187], v[96:99]
	v_mfma_f32_16x16x32_bf16 v[80:83], v[128:131], v[192:195], v[80:83]
	v_mfma_f32_16x16x32_bf16 v[72:75], v[136:139], v[192:195], v[72:75]
	v_mfma_f32_16x16x32_bf16 v[124:127], v[132:135], v[172:175], v[124:127]
	v_mfma_f32_16x16x32_bf16 v[120:123], v[140:143], v[172:175], v[120:123]
	v_mfma_f32_16x16x32_bf16 v[116:119], v[132:135], v[180:183], v[116:119]
	v_mfma_f32_16x16x32_bf16 v[112:115], v[140:143], v[180:183], v[112:115]
	v_mfma_f32_16x16x32_bf16 v[108:111], v[132:135], v[188:191], v[108:111]
	v_mfma_f32_16x16x32_bf16 v[96:99], v[140:143], v[188:191], v[96:99]
	v_mfma_f32_16x16x32_bf16 v[80:83], v[132:135], v[196:199], v[80:83]
	v_mfma_f32_16x16x32_bf16 v[72:75], v[140:143], v[196:199], v[72:75]
	v_mfma_f32_16x16x32_bf16 v[104:107], v[200:203], v[168:171], v[104:107]
	v_mfma_f32_16x16x32_bf16 v[100:103], v[208:211], v[168:171], v[100:103]
	v_mfma_f32_16x16x32_bf16 v[92:95], v[200:203], v[176:179], v[92:95]
	v_mfma_f32_16x16x32_bf16 v[88:91], v[208:211], v[176:179], v[88:91]
	v_mfma_f32_16x16x32_bf16 v[84:87], v[200:203], v[184:187], v[84:87]
	v_mfma_f32_16x16x32_bf16 v[76:79], v[208:211], v[184:187], v[76:79]
	v_mfma_f32_16x16x32_bf16 v[68:71], v[200:203], v[192:195], v[68:71]
	v_mfma_f32_16x16x32_bf16 v[64:67], v[208:211], v[192:195], v[64:67]
	v_mfma_f32_16x16x32_bf16 v[104:107], v[204:207], v[172:175], v[104:107]
	v_mfma_f32_16x16x32_bf16 v[100:103], v[212:215], v[172:175], v[100:103]
	v_mfma_f32_16x16x32_bf16 v[92:95], v[204:207], v[180:183], v[92:95]
	v_mfma_f32_16x16x32_bf16 v[88:91], v[212:215], v[180:183], v[88:91]
	v_mfma_f32_16x16x32_bf16 v[84:87], v[204:207], v[188:191], v[84:87]
	v_mfma_f32_16x16x32_bf16 v[76:79], v[212:215], v[188:191], v[76:79]
	v_mfma_f32_16x16x32_bf16 v[68:71], v[204:207], v[196:199], v[68:71]
	v_mfma_f32_16x16x32_bf16 v[64:67], v[212:215], v[196:199], v[64:67]
	s_setprio 0
	s_barrier
	ds_read_b128 v[168:171], v166 offset:16384
	ds_read_b128 v[172:175], v166 offset:17408
	ds_read_b128 v[176:179], v166 offset:18432
	ds_read_b128 v[180:183], v166 offset:19456
	ds_read_b128 v[184:187], v166 offset:20480
	ds_read_b128 v[188:191], v166 offset:21504
	ds_read_b128 v[192:195], v166 offset:22528
	ds_read_b128 v[196:199], v166 offset:23552
	s_add_i32 s44, s72, s58
	v_lshl_add_u64 v[162:163], s[48:49], 0, v[146:147]
	s_mov_b32 m0, s44
	s_nop 0
	global_load_lds_dwordx4 v[162:163], off
	v_lshl_add_u64 v[216:217], s[48:49], 0, v[150:151]
	s_add_i32 m0, s44, 0x2000
	s_nop 0
	global_load_lds_dwordx4 v[216:217], off
	s_mov_b32 m0, s59
	v_lshl_add_u64 v[218:219], s[50:51], 0, v[144:145]
	global_load_lds_dwordx4 v[218:219], off
	v_lshl_add_u64 v[220:221], s[50:51], 0, v[148:149]
	s_mov_b32 m0, s60
	s_nop 0
	global_load_lds_dwordx4 v[220:221], off
	s_add_u32 s44, s48, 0x40000
	s_addc_u32 s45, s49, 0
	s_add_i32 s83, s73, s58
	v_lshl_add_u64 v[254:255], s[44:45], 0, v[146:147]
	s_mov_b32 m0, s83
	s_nop 0
	global_load_lds_dwordx4 v[254:255], off
	v_lshl_add_u64 v[254:255], s[44:45], 0, v[150:151]
	s_add_i32 m0, s83, 0x2000
	s_nop 0
	global_load_lds_dwordx4 v[254:255], off
	s_waitcnt vmcnt(8)
	s_waitcnt lgkmcnt(0)
	s_barrier
	s_setprio 1
	v_mfma_f32_16x16x32_bf16 v[60:63], v[128:131], v[168:171], v[60:63]
	v_mfma_f32_16x16x32_bf16 v[56:59], v[136:139], v[168:171], v[56:59]
	v_mfma_f32_16x16x32_bf16 v[48:51], v[128:131], v[176:179], v[48:51]
	v_mfma_f32_16x16x32_bf16 v[40:43], v[136:139], v[176:179], v[40:43]
	v_mfma_f32_16x16x32_bf16 v[32:35], v[128:131], v[184:187], v[32:35]
	v_mfma_f32_16x16x32_bf16 v[24:27], v[136:139], v[184:187], v[24:27]
	v_mfma_f32_16x16x32_bf16 v[16:19], v[128:131], v[192:195], v[16:19]
	v_mfma_f32_16x16x32_bf16 v[8:11], v[136:139], v[192:195], v[8:11]
	v_mfma_f32_16x16x32_bf16 v[60:63], v[132:135], v[172:175], v[60:63]
	v_mfma_f32_16x16x32_bf16 v[56:59], v[140:143], v[172:175], v[56:59]
	v_mfma_f32_16x16x32_bf16 v[48:51], v[132:135], v[180:183], v[48:51]
	v_mfma_f32_16x16x32_bf16 v[40:43], v[140:143], v[180:183], v[40:43]
	v_mfma_f32_16x16x32_bf16 v[32:35], v[132:135], v[188:191], v[32:35]
	v_mfma_f32_16x16x32_bf16 v[24:27], v[140:143], v[188:191], v[24:27]
	v_mfma_f32_16x16x32_bf16 v[16:19], v[132:135], v[196:199], v[16:19]
	v_mfma_f32_16x16x32_bf16 v[8:11], v[140:143], v[196:199], v[8:11]
	v_mfma_f32_16x16x32_bf16 v[52:55], v[200:203], v[168:171], v[52:55]
	v_mfma_f32_16x16x32_bf16 v[44:47], v[208:211], v[168:171], v[44:47]
	v_mfma_f32_16x16x32_bf16 v[36:39], v[200:203], v[176:179], v[36:39]
	v_mfma_f32_16x16x32_bf16 v[28:31], v[208:211], v[176:179], v[28:31]
	v_mfma_f32_16x16x32_bf16 v[20:23], v[200:203], v[184:187], v[20:23]
	v_mfma_f32_16x16x32_bf16 v[12:15], v[208:211], v[184:187], v[12:15]
	v_mfma_f32_16x16x32_bf16 v[4:7], v[200:203], v[192:195], v[4:7]
	v_mfma_f32_16x16x32_bf16 v[0:3], v[208:211], v[192:195], v[0:3]
	v_mfma_f32_16x16x32_bf16 v[52:55], v[204:207], v[172:175], v[52:55]
	v_mfma_f32_16x16x32_bf16 v[44:47], v[212:215], v[172:175], v[44:47]
	v_mfma_f32_16x16x32_bf16 v[36:39], v[204:207], v[180:183], v[36:39]
	v_mfma_f32_16x16x32_bf16 v[28:31], v[212:215], v[180:183], v[28:31]
	v_mfma_f32_16x16x32_bf16 v[20:23], v[204:207], v[188:191], v[20:23]
	v_mfma_f32_16x16x32_bf16 v[12:15], v[212:215], v[188:191], v[12:15]
	v_mfma_f32_16x16x32_bf16 v[4:7], v[204:207], v[196:199], v[4:7]
	v_mfma_f32_16x16x32_bf16 v[0:3], v[212:215], v[196:199], v[0:3]
	s_setprio 0
	s_add_i32 s83, 0, 0x18000
	v_add_u32_e32 v140, s83, v164
	s_barrier
; #define PG8_STAGE(bufoff, gbase, voff) do { _Pragma("unroll") for (int _i = 0; _i < 2; ++_i) \
;         __builtin_amdgcn_global_load_lds((const unsigned*)((const char*)(gbase) + (voff)[_i]), (LAS unsigned*)(lds + (bufoff) + ldsw + _i * 8192), 16, 0, 0); } while (0)
; #define PG8_LDA(dst, b, h) do { _Pragma("unroll") for (int m = 0; m < 4; ++m) _Pragma("unroll") for (int k = 0; k < 2; ++k) dst[m][k] = *(const LAS bf16x8*)(lds + PG8_SA(b, h) + aoff + m * 2048 + k * 1024); } while (0)
; #define PG8_LDB(dst, b, h) do { _Pragma("unroll") for (int n = 0; n < 2; ++n) _Pragma("unroll") for (int k = 0; k < 2; ++k) dst[n][k] = *(const LAS bf16x8*)(lds + PG8_SB(b, h) + boff + n * 2048 + k * 1024); } while (0)
; #define PG8_MMA(ai, bj, At, Bt) do { __builtin_amdgcn_s_setprio(1); _Pragma("unroll") for (int m = 0; m < 4; ++m) _Pragma("unroll") for (int n = 0; n < 2; ++n) _Pragma("unroll") for (int k = 0; k < 2; ++k) \
;         acc[ai][bj][m][n] = __builtin_amdgcn_mfma_f32_16x16x32_bf16(Bt[n][k], At[m][k], acc[ai][bj][m][n], 0, 0, 0); __builtin_amdgcn_s_setprio(0); } while (0)
; #define PG8_WAIT_V(n) asm volatile("s_waitcnt vmcnt(" #n ")" ::: "memory")
; #define PG8_WAIT_L(n) asm volatile("s_waitcnt lgkmcnt(" #n ")" ::: "memory")
; #define PG8_BAR __builtin_amdgcn_s_barrier()
; #define PG8_SCHED __builtin_amdgcn_sched_barrier(0)
; template <class Epi>
; __device__ __forceinline__ void gemm_phase(LAS unsigned char* lds, const Gemm g, const StaticOrder& S, const Epi& E, int wv) {
;     ...
;             PG8_LDB(B0, 1, 0); PG8_SCHED; PG8_LDA(At, 1, 0); PG8_STAGE(PG8_SA(0, 1), a2 + hstep, voffA);
;             PG8_WAIT_L(8); PG8_BAR; PG8_WAIT_L(0); PG8_MMA(0, 0, At, B0); PG8_BAR; PG8_SCHED;
;             PG8_LDB(B1, 1, 1); PG8_STAGE(PG8_SB(1, 0), b3, voffB);
;             PG8_BAR; PG8_WAIT_L(0); PG8_MMA(0, 1, At, B1); PG8_BAR;
;             PG8_LDA(At, 1, 1); PG8_STAGE(PG8_SA(1, 0), a3, voffA);
;             PG8_BAR; PG8_WAIT_L(0); PG8_MMA(1, 0, At, B0); PG8_BAR; PG8_SCHED;
;             PG8_STAGE(PG8_SB(1, 1), b3 + hstep, voffB);
;             PG8_WAIT_V(6); PG8_BAR; PG8_MMA(1, 1, At, B1); PG8_BAR;
	ds_read_b128 v[128:131], v140
	ds_read_b128 v[132:135], v140 offset:1024
	ds_read_b128 v[136:139], v140 offset:2048
	ds_read_b128 v[140:143], v140 offset:3072
	s_add_u32 s44, s50, 0x40000
	s_addc_u32 s45, s51, 0
	ds_read_b128 v[168:171], v166 offset:32768
	ds_read_b128 v[172:175], v166 offset:33792
	ds_read_b128 v[176:179], v166 offset:34816
	ds_read_b128 v[180:183], v166 offset:35840
	ds_read_b128 v[184:187], v166 offset:36864
	ds_read_b128 v[188:191], v166 offset:37888
	ds_read_b128 v[192:195], v166 offset:38912
	ds_read_b128 v[196:199], v166 offset:39936
	s_mov_b32 m0, s61
	v_lshl_add_u64 v[252:253], s[44:45], 0, v[144:145]
	global_load_lds_dwordx4 v[252:253], off
	v_lshl_add_u64 v[252:253], s[44:45], 0, v[148:149]
	s_mov_b32 m0, s64
	s_nop 0
	global_load_lds_dwordx4 v[252:253], off
	s_add_i32 s50, 0, 0x1c000
	v_add_u32_e32 v152, s50, v164
	ds_read_b128 v[200:203], v152
	ds_read_b128 v[204:207], v152 offset:1024
	ds_read_b128 v[208:211], v152 offset:2048
	ds_read_b128 v[212:215], v152 offset:3072
	s_waitcnt vmcnt(8)
	s_waitcnt lgkmcnt(0)
	s_barrier
	s_setprio 1
	v_mfma_f32_16x16x32_bf16 v[124:127], v[128:131], v[168:171], v[124:127]
	v_mfma_f32_16x16x32_bf16 v[120:123], v[136:139], v[168:171], v[120:123]
	v_mfma_f32_16x16x32_bf16 v[116:119], v[128:131], v[176:179], v[116:119]
	v_mfma_f32_16x16x32_bf16 v[112:115], v[136:139], v[176:179], v[112:115]
	v_mfma_f32_16x16x32_bf16 v[108:111], v[128:131], v[184:187], v[108:111]
	v_mfma_f32_16x16x32_bf16 v[96:99], v[136:139], v[184:187], v[96:99]
	v_mfma_f32_16x16x32_bf16 v[80:83], v[128:131], v[192:195], v[80:83]
	v_mfma_f32_16x16x32_bf16 v[72:75], v[136:139], v[192:195], v[72:75]
	v_mfma_f32_16x16x32_bf16 v[124:127], v[132:135], v[172:175], v[124:127]
	v_mfma_f32_16x16x32_bf16 v[120:123], v[140:143], v[172:175], v[120:123]
	v_mfma_f32_16x16x32_bf16 v[116:119], v[132:135], v[180:183], v[116:119]
	v_mfma_f32_16x16x32_bf16 v[112:115], v[140:143], v[180:183], v[112:115]
	v_mfma_f32_16x16x32_bf16 v[108:111], v[132:135], v[188:191], v[108:111]
	v_mfma_f32_16x16x32_bf16 v[96:99], v[140:143], v[188:191], v[96:99]
	v_mfma_f32_16x16x32_bf16 v[80:83], v[132:135], v[196:199], v[80:83]
	v_mfma_f32_16x16x32_bf16 v[72:75], v[140:143], v[196:199], v[72:75]
	v_mfma_f32_16x16x32_bf16 v[104:107], v[200:203], v[168:171], v[104:107]
	v_mfma_f32_16x16x32_bf16 v[100:103], v[208:211], v[168:171], v[100:103]
	v_mfma_f32_16x16x32_bf16 v[92:95], v[200:203], v[176:179], v[92:95]
	v_mfma_f32_16x16x32_bf16 v[88:91], v[208:211], v[176:179], v[88:91]
	v_mfma_f32_16x16x32_bf16 v[84:87], v[200:203], v[184:187], v[84:87]
	v_mfma_f32_16x16x32_bf16 v[76:79], v[208:211], v[184:187], v[76:79]
	v_mfma_f32_16x16x32_bf16 v[68:71], v[200:203], v[192:195], v[68:71]
	v_mfma_f32_16x16x32_bf16 v[64:67], v[208:211], v[192:195], v[64:67]
	v_mfma_f32_16x16x32_bf16 v[104:107], v[204:207], v[172:175], v[104:107]
	v_mfma_f32_16x16x32_bf16 v[100:103], v[212:215], v[172:175], v[100:103]
	v_mfma_f32_16x16x32_bf16 v[92:95], v[204:207], v[180:183], v[92:95]
	v_mfma_f32_16x16x32_bf16 v[88:91], v[212:215], v[180:183], v[88:91]
	v_mfma_f32_16x16x32_bf16 v[84:87], v[204:207], v[188:191], v[84:87]
	v_mfma_f32_16x16x32_bf16 v[76:79], v[212:215], v[188:191], v[76:79]
	v_mfma_f32_16x16x32_bf16 v[68:71], v[204:207], v[196:199], v[68:71]
	v_mfma_f32_16x16x32_bf16 v[64:67], v[212:215], v[196:199], v[64:67]
	s_setprio 0
	s_barrier
	ds_read_b128 v[168:171], v166 offset:49152
	ds_read_b128 v[172:175], v166 offset:50176
	ds_read_b128 v[176:179], v166 offset:51200
	ds_read_b128 v[180:183], v166 offset:52224
	ds_read_b128 v[184:187], v166 offset:53248
	ds_read_b128 v[188:191], v166 offset:54272
	ds_read_b128 v[192:195], v166 offset:55296
	ds_read_b128 v[196:199], v166 offset:56320
	s_add_i32 s44, s83, s58
	v_lshl_add_u64 v[162:163], v[162:163], 0, s[16:17]
	s_mov_b32 m0, s44
	s_nop 0
	global_load_lds_dwordx4 v[162:163], off
	v_lshl_add_u64 v[162:163], v[216:217], 0, s[16:17]
	s_add_i32 m0, s44, 0x2000
	s_nop 0
	global_load_lds_dwordx4 v[162:163], off
	s_mov_b32 m0, s67
	v_lshl_add_u64 v[162:163], v[218:219], 0, s[16:17]
	global_load_lds_dwordx4 v[162:163], off
	v_lshl_add_u64 v[162:163], v[220:221], 0, s[16:17]
	s_mov_b32 m0, s68
	s_nop 0
	global_load_lds_dwordx4 v[162:163], off
	s_add_u32 s44, s48, 0x40080
	s_addc_u32 s45, s49, 0
	s_add_i32 s48, s50, s58
	v_lshl_add_u64 v[254:255], s[44:45], 0, v[146:147]
	s_mov_b32 m0, s48
	s_nop 0
	global_load_lds_dwordx4 v[254:255], off
	v_lshl_add_u64 v[254:255], s[44:45], 0, v[150:151]
	s_add_i32 m0, s48, 0x2000
	s_nop 0
	global_load_lds_dwordx4 v[254:255], off
	s_waitcnt vmcnt(8)
	s_waitcnt lgkmcnt(0)
	s_barrier
; __device__ __forceinline__ int lane_fresh() { unsigned m = ~0u; asm volatile("" : "+s"(m)); return (int)__builtin_amdgcn_mbcnt_hi(m, __builtin_amdgcn_mbcnt_lo(m, 0u)); }
; __device__ __forceinline__ unsigned pk2(float lo, float hi) { unsigned r; asm("v_cvt_pk_bf16_f32 %0, %1, %2" : "=v"(r) : "v"(lo), "v"(hi)); return r; }
; #define PG8_STAGE(bufoff, gbase, voff) do { _Pragma("unroll") for (int _i = 0; _i < 2; ++_i) \
;         __builtin_amdgcn_global_load_lds((const unsigned*)((const char*)(gbase) + (voff)[_i]), (LAS unsigned*)(lds + (bufoff) + ldsw + _i * 8192), 16, 0, 0); } while (0)
; #define PG8_WAIT_V(n) asm volatile("s_waitcnt vmcnt(" #n ")" ::: "memory")
; #define PG8_BAR __builtin_amdgcn_s_barrier()
; template <class Epi>
; __device__ __forceinline__ void gemm_phase(LAS unsigned char* lds, const Gemm g, const StaticOrder& S, const Epi& E, int wv) {
;     ...
;             PG8_STAGE(PG8_SB(1, 1), b3 + hstep, voffB);
;             PG8_WAIT_V(6); PG8_BAR; PG8_MMA(1, 1, At, B1); PG8_BAR;
;         }
;         { const int ln2 = lane_fresh();
;           E(acc, cur, wr, wc, ln2 & 15, ln2 >> 4); }
;     __device__ __forceinline__ void operator()(const f32x4 (&acc)[2][2][4][2], const Unit& u, int wr, int wc, int fr, int fq) const {
;         const float* gate = (u.pm >= 64) ? gate1 : gate0;
;         f32x4 gv[2][2];
; #pragma unroll
;         for (int bj = 0; bj < 2; ++bj)
; #pragma unroll
;             for (int n = 0; n < 2; ++n) gv[bj][n] = *(const f32x4*)(gate + u.pn * 256 + bj * 128 + wc * 32 + n * 16 + 4 * fq);
; #pragma unroll
;         for (int ai = 0; ai < 2; ++ai)
; #pragma unroll
;             for (int m = 0; m < 4; ++m) {
;                 const size_t row = (size_t)u.pm * 256 + ai * 128 + wr * 64 + 4 * fr + m;
; #pragma unroll
;                 for (int bj = 0; bj < 2; ++bj)
; #pragma unroll
;                     for (int n = 0; n < 2; ++n) {
;                         const f32x4 v = gv[bj][n] * acc[ai][bj][m][n];
;                         u32x2 w; w.x = pk2(v[0], v[1]); w.y = pk2(v[2], v[3]);
;                         *(u32x2*)(O + row * D + u.pn * 256 + bj * 128 + wc * 32 + n * 16 + 4 * fq) = w;
;                     }
	s_setprio 1
	v_mfma_f32_16x16x32_bf16 v[60:63], v[128:131], v[168:171], v[60:63]
	v_mfma_f32_16x16x32_bf16 v[56:59], v[136:139], v[168:171], v[56:59]
	v_mfma_f32_16x16x32_bf16 v[48:51], v[128:131], v[176:179], v[48:51]
	v_mfma_f32_16x16x32_bf16 v[40:43], v[136:139], v[176:179], v[40:43]
	v_mfma_f32_16x16x32_bf16 v[32:35], v[128:131], v[184:187], v[32:35]
	v_mfma_f32_16x16x32_bf16 v[24:27], v[136:139], v[184:187], v[24:27]
	v_mfma_f32_16x16x32_bf16 v[16:19], v[128:131], v[192:195], v[16:19]
	v_mfma_f32_16x16x32_bf16 v[8:11], v[136:139], v[192:195], v[8:11]
	v_mfma_f32_16x16x32_bf16 v[60:63], v[132:135], v[172:175], v[60:63]
	v_mfma_f32_16x16x32_bf16 v[56:59], v[140:143], v[172:175], v[56:59]
	v_mfma_f32_16x16x32_bf16 v[48:51], v[132:135], v[180:183], v[48:51]
	v_mfma_f32_16x16x32_bf16 v[40:43], v[140:143], v[180:183], v[40:43]
	v_mfma_f32_16x16x32_bf16 v[32:35], v[132:135], v[188:191], v[32:35]
	v_mfma_f32_16x16x32_bf16 v[24:27], v[140:143], v[188:191], v[24:27]
	v_mfma_f32_16x16x32_bf16 v[16:19], v[132:135], v[196:199], v[16:19]
	v_mfma_f32_16x16x32_bf16 v[8:11], v[140:143], v[196:199], v[8:11]
	v_mfma_f32_16x16x32_bf16 v[52:55], v[200:203], v[168:171], v[52:55]
	v_mfma_f32_16x16x32_bf16 v[44:47], v[208:211], v[168:171], v[44:47]
	v_mfma_f32_16x16x32_bf16 v[36:39], v[200:203], v[176:179], v[36:39]
	v_mfma_f32_16x16x32_bf16 v[28:31], v[208:211], v[176:179], v[28:31]
	v_mfma_f32_16x16x32_bf16 v[20:23], v[200:203], v[184:187], v[20:23]
	v_mfma_f32_16x16x32_bf16 v[12:15], v[208:211], v[184:187], v[12:15]
	v_mfma_f32_16x16x32_bf16 v[4:7], v[200:203], v[192:195], v[4:7]
	v_mfma_f32_16x16x32_bf16 v[0:3], v[208:211], v[192:195], v[0:3]
	v_mfma_f32_16x16x32_bf16 v[52:55], v[204:207], v[172:175], v[52:55]
	v_mfma_f32_16x16x32_bf16 v[44:47], v[212:215], v[172:175], v[44:47]
	v_mfma_f32_16x16x32_bf16 v[36:39], v[204:207], v[180:183], v[36:39]
	v_mfma_f32_16x16x32_bf16 v[28:31], v[212:215], v[180:183], v[28:31]
	v_mfma_f32_16x16x32_bf16 v[20:23], v[204:207], v[188:191], v[20:23]
	v_mfma_f32_16x16x32_bf16 v[12:15], v[212:215], v[188:191], v[12:15]
	v_mfma_f32_16x16x32_bf16 v[4:7], v[204:207], v[196:199], v[4:7]
	v_mfma_f32_16x16x32_bf16 v[0:3], v[212:215], v[196:199], v[0:3]
	s_setprio 0
	s_add_i32 s82, s82, 2
	s_add_u32 s80, s80, 0x100
	s_addc_u32 s81, s81, 0
	s_cmp_gt_u32 s82, 13
	s_mov_b64 s[44:45], s[46:47]
	s_barrier
	s_cbranch_scc0 .LBB0_846
	s_mov_b32 s35, -1
	s_cmp_gt_i32 s42, 63
	v_mbcnt_lo_u32_b32 v128, s35, 0
	v_mbcnt_hi_u32_b32 v152, s35, v128
	s_cselect_b32 s35, s74, 0x1642000
	s_add_u32 s35, s6, s35
	s_addc_u32 s37, s7, 0
	s_lshl_b32 s44, s8, 8
	s_ashr_i32 s45, s44, 31
	s_lshl_b64 s[46:47], s[44:45], 2
	s_add_u32 s8, s35, s46
	s_addc_u32 s35, s37, s47
	s_lshl_b32 s37, s66, 2
	v_lshrrev_b32_e32 v128, 2, v152
	s_add_u32 s46, s8, s37
	v_and_b32_e32 v162, 28, v128
	s_addc_u32 s47, s35, 0
	v_lshlrev_b32_e32 v128, 2, v162
	s_nop 0
	s_ashr_i32 s43, s42, 31
	s_lshl_b64 s[42:43], s[42:43], 8
	s_add_u32 s8, s42, s65
	v_lshlrev_b32_e32 v163, 2, v152
	s_addc_u32 s35, s43, s69
	v_bfe_u32 v222, v152, 5, 1
	v_bfe_u32 v152, v152, 4, 1
	v_lshlrev_b32_e32 v222, 4, v222
	v_lshl_or_b32 v152, v152, 5, v222
	v_and_or_b32 v162, v163, 60, s8
	v_mov_b32_e32 v163, s35
	v_lshlrev_b64 v[162:163], 11, v[162:163]
	v_lshl_add_u64 v[162:163], s[14:15], 0, v[162:163]
	s_lshl_b32 s8, s66, 1
	v_lshl_add_u64 v[162:163], s[44:45], 1, v[162:163]
	v_lshl_add_u64 v[162:163], v[162:163], 0, s[8:9]
	v_lshl_add_u64 v[162:163], v[162:163], 0, v[152:153]
	v_lshl_add_u64 v[168:169], v[162:163], 0, s[18:19]
	v_lshl_add_u64 v[170:171], v[162:163], 0, s[12:13]
	s_mov_b32 s8, s34
	s_nop 0
	v_lshl_add_u64 v[222:223], v[162:163], 0, s[28:29]
	s_mov_b32 s42, s36
	s_mov_b64 s[46:47], s[40:41]
	s_mov_b64 s[44:45], s[38:39]
	v_pk_mul_f32 v[124:125], v[124:125], v[236:237]
	v_pk_mul_f32 v[126:127], v[126:127], v[238:239]
	v_pk_mul_f32 v[120:121], v[120:121], v[232:233]
	v_pk_mul_f32 v[122:123], v[122:123], v[234:235]
	v_cvt_pk_bf16_f32 v124, v124, v125
	v_cvt_pk_bf16_f32 v125, v126, v127
	v_cvt_pk_bf16_f32 v126, v120, v121
	v_cvt_pk_bf16_f32 v127, v122, v123
	v_pk_mul_f32 v[104:105], v[104:105], v[228:229]
	v_pk_mul_f32 v[106:107], v[106:107], v[230:231]
	v_pk_mul_f32 v[100:101], v[100:101], v[224:225]
	v_pk_mul_f32 v[102:103], v[102:103], v[226:227]
	v_permlane16_swap_b32_e32 v124, v126
	v_permlane16_swap_b32_e32 v125, v127
	global_store_dwordx4 v[162:163], v[124:127], off
	v_cvt_pk_bf16_f32 v104, v104, v105
	v_cvt_pk_bf16_f32 v105, v106, v107
	v_cvt_pk_bf16_f32 v106, v100, v101
	v_cvt_pk_bf16_f32 v107, v102, v103
	v_pk_mul_f32 v[116:117], v[116:117], v[236:237]
	v_pk_mul_f32 v[118:119], v[118:119], v[238:239]
	v_pk_mul_f32 v[112:113], v[112:113], v[232:233]
	v_pk_mul_f32 v[114:115], v[114:115], v[234:235]
	v_permlane16_swap_b32_e32 v104, v106
	v_permlane16_swap_b32_e32 v105, v107
	global_store_dwordx4 v[162:163], v[104:107], off offset:256
	v_cvt_pk_bf16_f32 v116, v116, v117
	v_cvt_pk_bf16_f32 v117, v118, v119
	v_cvt_pk_bf16_f32 v118, v112, v113
	v_cvt_pk_bf16_f32 v119, v114, v115
	v_pk_mul_f32 v[92:93], v[92:93], v[228:229]
	v_pk_mul_f32 v[94:95], v[94:95], v[230:231]
	v_pk_mul_f32 v[88:89], v[88:89], v[224:225]
	v_pk_mul_f32 v[90:91], v[90:91], v[226:227]
	v_permlane16_swap_b32_e32 v116, v118
	v_permlane16_swap_b32_e32 v117, v119
	global_store_dwordx4 v[162:163], v[116:119], off offset:2048
	v_cvt_pk_bf16_f32 v92, v92, v93
	v_cvt_pk_bf16_f32 v93, v94, v95
	v_cvt_pk_bf16_f32 v94, v88, v89
	v_cvt_pk_bf16_f32 v95, v90, v91
	v_pk_mul_f32 v[108:109], v[108:109], v[236:237]
; __device__ __forceinline__ unsigned pk2(float lo, float hi) { unsigned r; asm("v_cvt_pk_bf16_f32 %0, %1, %2" : "=v"(r) : "v"(lo), "v"(hi)); return r; }
; #define PG8_WAIT_V(n) asm volatile("s_waitcnt vmcnt(" #n ")" ::: "memory")
; #define PG8_BAR __builtin_amdgcn_s_barrier()
; template <class Epi>
; __device__ __forceinline__ void gemm_phase(LAS unsigned char* lds, const Gemm g, const StaticOrder& S, const Epi& E, int wv) {
;     ...
;         if (!has_next) break;
; #pragma unroll
;         for (int a = 0; a < 2; ++a)
; #pragma unroll
;             for (int b = 0; b < 2; ++b)
; #pragma unroll
;                 for (int m = 0; m < 4; ++m)
; #pragma unroll
;                     for (int n = 0; n < 2; ++n) acc[a][b][m][n] = (f32x4){0.f, 0.f, 0.f, 0.f};
;         cur = nxt; cA = nA; cB = nB; ++ui;
;     }
;     PG8_WAIT_V(0);
;     if (wr == 0) PG8_BAR;
;     PG8_BAR;
;     __device__ __forceinline__ void operator()(const f32x4 (&acc)[2][2][4][2], const Unit& u, int wr, int wc, int fr, int fq) const {
;     ...
;         for (int ai = 0; ai < 2; ++ai)
; #pragma unroll
;             for (int m = 0; m < 4; ++m) {
;                 const size_t row = (size_t)u.pm * 256 + ai * 128 + wr * 64 + 4 * fr + m;
; #pragma unroll
;                 for (int bj = 0; bj < 2; ++bj)
; #pragma unroll
;                     for (int n = 0; n < 2; ++n) {
;                         const f32x4 v = gv[bj][n] * acc[ai][bj][m][n];
;                         u32x2 w; w.x = pk2(v[0], v[1]); w.y = pk2(v[2], v[3]);
;                         *(u32x2*)(O + row * D + u.pn * 256 + bj * 128 + wc * 32 + n * 16 + 4 * fq) = w;
;                     }
	v_pk_mul_f32 v[110:111], v[110:111], v[238:239]
	v_pk_mul_f32 v[96:97], v[96:97], v[232:233]
	v_pk_mul_f32 v[98:99], v[98:99], v[234:235]
	v_permlane16_swap_b32_e32 v92, v94
	v_permlane16_swap_b32_e32 v93, v95
	global_store_dwordx4 v[162:163], v[92:95], off offset:2304
	v_cvt_pk_bf16_f32 v108, v108, v109
	v_cvt_pk_bf16_f32 v109, v110, v111
	v_cvt_pk_bf16_f32 v110, v96, v97
	v_cvt_pk_bf16_f32 v111, v98, v99
	v_pk_mul_f32 v[84:85], v[84:85], v[228:229]
	v_pk_mul_f32 v[86:87], v[86:87], v[230:231]
	v_pk_mul_f32 v[76:77], v[76:77], v[224:225]
	v_pk_mul_f32 v[78:79], v[78:79], v[226:227]
	v_permlane16_swap_b32_e32 v108, v110
	v_permlane16_swap_b32_e32 v109, v111
	global_store_dwordx4 v[168:169], v[108:111], off
	v_cvt_pk_bf16_f32 v84, v84, v85
	v_cvt_pk_bf16_f32 v85, v86, v87
	v_cvt_pk_bf16_f32 v86, v76, v77
	v_cvt_pk_bf16_f32 v87, v78, v79
	v_pk_mul_f32 v[80:81], v[80:81], v[236:237]
	v_pk_mul_f32 v[82:83], v[82:83], v[238:239]
	v_pk_mul_f32 v[72:73], v[72:73], v[232:233]
	v_pk_mul_f32 v[74:75], v[74:75], v[234:235]
	v_permlane16_swap_b32_e32 v84, v86
	v_permlane16_swap_b32_e32 v85, v87
	global_store_dwordx4 v[168:169], v[84:87], off offset:256
	v_cvt_pk_bf16_f32 v80, v80, v81
	v_cvt_pk_bf16_f32 v81, v82, v83
	v_cvt_pk_bf16_f32 v82, v72, v73
	v_cvt_pk_bf16_f32 v83, v74, v75
	v_pk_mul_f32 v[68:69], v[68:69], v[228:229]
	v_pk_mul_f32 v[70:71], v[70:71], v[230:231]
	v_pk_mul_f32 v[64:65], v[64:65], v[224:225]
	v_pk_mul_f32 v[66:67], v[66:67], v[226:227]
	v_permlane16_swap_b32_e32 v80, v82
	v_permlane16_swap_b32_e32 v81, v83
	global_store_dwordx4 v[168:169], v[80:83], off offset:2048
	v_cvt_pk_bf16_f32 v68, v68, v69
	v_cvt_pk_bf16_f32 v69, v70, v71
	v_cvt_pk_bf16_f32 v70, v64, v65
	v_cvt_pk_bf16_f32 v71, v66, v67
	v_pk_mul_f32 v[60:61], v[60:61], v[236:237]
	v_pk_mul_f32 v[62:63], v[62:63], v[238:239]
	v_pk_mul_f32 v[56:57], v[56:57], v[232:233]
	v_pk_mul_f32 v[58:59], v[58:59], v[234:235]
	v_permlane16_swap_b32_e32 v68, v70
	v_permlane16_swap_b32_e32 v69, v71
	global_store_dwordx4 v[168:169], v[68:71], off offset:2304
	v_cvt_pk_bf16_f32 v60, v60, v61
	v_cvt_pk_bf16_f32 v61, v62, v63
	v_cvt_pk_bf16_f32 v62, v56, v57
	v_cvt_pk_bf16_f32 v63, v58, v59
	v_pk_mul_f32 v[52:53], v[52:53], v[228:229]
	v_pk_mul_f32 v[54:55], v[54:55], v[230:231]
	v_pk_mul_f32 v[44:45], v[44:45], v[224:225]
	v_pk_mul_f32 v[46:47], v[46:47], v[226:227]
	v_permlane16_swap_b32_e32 v60, v62
	v_permlane16_swap_b32_e32 v61, v63
	global_store_dwordx4 v[170:171], v[60:63], off
	v_cvt_pk_bf16_f32 v52, v52, v53
	v_cvt_pk_bf16_f32 v53, v54, v55
	v_cvt_pk_bf16_f32 v54, v44, v45
	v_cvt_pk_bf16_f32 v55, v46, v47
	v_pk_mul_f32 v[48:49], v[48:49], v[236:237]
	v_pk_mul_f32 v[50:51], v[50:51], v[238:239]
	v_pk_mul_f32 v[40:41], v[40:41], v[232:233]
	v_pk_mul_f32 v[42:43], v[42:43], v[234:235]
	v_permlane16_swap_b32_e32 v52, v54
	v_permlane16_swap_b32_e32 v53, v55
	global_store_dwordx4 v[170:171], v[52:55], off offset:256
	v_cvt_pk_bf16_f32 v48, v48, v49
	v_cvt_pk_bf16_f32 v49, v50, v51
	v_cvt_pk_bf16_f32 v50, v40, v41
	v_cvt_pk_bf16_f32 v51, v42, v43
	v_pk_mul_f32 v[36:37], v[36:37], v[228:229]
	v_pk_mul_f32 v[38:39], v[38:39], v[230:231]
	v_pk_mul_f32 v[28:29], v[28:29], v[224:225]
	v_pk_mul_f32 v[30:31], v[30:31], v[226:227]
	v_permlane16_swap_b32_e32 v48, v50
	v_permlane16_swap_b32_e32 v49, v51
	global_store_dwordx4 v[170:171], v[48:51], off offset:2048
	v_cvt_pk_bf16_f32 v36, v36, v37
	v_cvt_pk_bf16_f32 v37, v38, v39
	v_cvt_pk_bf16_f32 v38, v28, v29
	v_cvt_pk_bf16_f32 v39, v30, v31
	v_pk_mul_f32 v[32:33], v[32:33], v[236:237]
	v_pk_mul_f32 v[34:35], v[34:35], v[238:239]
	v_pk_mul_f32 v[24:25], v[24:25], v[232:233]
	v_pk_mul_f32 v[26:27], v[26:27], v[234:235]
	v_permlane16_swap_b32_e32 v36, v38
	v_permlane16_swap_b32_e32 v37, v39
	global_store_dwordx4 v[170:171], v[36:39], off offset:2304
	v_cvt_pk_bf16_f32 v32, v32, v33
	v_cvt_pk_bf16_f32 v33, v34, v35
	v_cvt_pk_bf16_f32 v34, v24, v25
	v_cvt_pk_bf16_f32 v35, v26, v27
	v_pk_mul_f32 v[20:21], v[20:21], v[228:229]
	v_pk_mul_f32 v[22:23], v[22:23], v[230:231]
	v_pk_mul_f32 v[12:13], v[12:13], v[224:225]
	v_pk_mul_f32 v[14:15], v[14:15], v[226:227]
	v_permlane16_swap_b32_e32 v32, v34
	v_permlane16_swap_b32_e32 v33, v35
	global_store_dwordx4 v[222:223], v[32:35], off
	v_cvt_pk_bf16_f32 v20, v20, v21
	v_cvt_pk_bf16_f32 v21, v22, v23
	v_cvt_pk_bf16_f32 v22, v12, v13
	v_cvt_pk_bf16_f32 v23, v14, v15
	v_pk_mul_f32 v[16:17], v[16:17], v[236:237]
	v_pk_mul_f32 v[18:19], v[18:19], v[238:239]
	v_pk_mul_f32 v[8:9], v[8:9], v[232:233]
	v_pk_mul_f32 v[10:11], v[10:11], v[234:235]
	v_permlane16_swap_b32_e32 v20, v22
	v_permlane16_swap_b32_e32 v21, v23
	global_store_dwordx4 v[222:223], v[20:23], off offset:256
	v_cvt_pk_bf16_f32 v16, v16, v17
	v_cvt_pk_bf16_f32 v17, v18, v19
	v_cvt_pk_bf16_f32 v18, v8, v9
	v_cvt_pk_bf16_f32 v19, v10, v11
	v_pk_mul_f32 v[4:5], v[4:5], v[228:229]
	v_pk_mul_f32 v[6:7], v[6:7], v[230:231]
	v_pk_mul_f32 v[0:1], v[0:1], v[224:225]
	v_pk_mul_f32 v[2:3], v[2:3], v[226:227]
	v_permlane16_swap_b32_e32 v16, v18
	v_permlane16_swap_b32_e32 v17, v19
	global_store_dwordx4 v[222:223], v[16:19], off offset:2048
	v_cvt_pk_bf16_f32 v4, v4, v5
	v_cvt_pk_bf16_f32 v5, v6, v7
	v_cvt_pk_bf16_f32 v6, v0, v1
	v_cvt_pk_bf16_f32 v7, v2, v3
	s_nop 1
	v_permlane16_swap_b32_e32 v4, v6
	v_permlane16_swap_b32_e32 v5, v7
	global_store_dwordx4 v[222:223], v[4:7], off offset:2304
	s_and_b64 vcc, exec, s[4:5]
	s_cbranch_vccz .LBB0_839
	s_waitcnt vmcnt(0)
	s_cmpk_gt_u32 s52, 0xff
	s_cbranch_scc1 .LBB0_850
	s_barrier

; #define PG8_STAGE(bufoff, gbase, voff) do { _Pragma("unroll") for (int _i = 0; _i < 2; ++_i) \
;         __builtin_amdgcn_global_load_lds((const unsigned*)((const char*)(gbase) + (voff)[_i]), (LAS unsigned*)(lds + (bufoff) + ldsw + _i * 8192), 16, 0, 0); } while (0)
; #define PG8_LDA(dst, b, h) do { _Pragma("unroll") for (int m = 0; m < 4; ++m) _Pragma("unroll") for (int k = 0; k < 2; ++k) dst[m][k] = *(const LAS bf16x8*)(lds + PG8_SA(b, h) + aoff + m * 2048 + k * 1024); } while (0)
; #define PG8_LDB(dst, b, h) do { _Pragma("unroll") for (int n = 0; n < 2; ++n) _Pragma("unroll") for (int k = 0; k < 2; ++k) dst[n][k] = *(const LAS bf16x8*)(lds + PG8_SB(b, h) + boff + n * 2048 + k * 1024); } while (0)
; #define PG8_WAIT_L(n) asm volatile("s_waitcnt lgkmcnt(" #n ")" ::: "memory")
; #define PG8_BAR __builtin_amdgcn_s_barrier()
; #define PG8_SCHED __builtin_amdgcn_sched_barrier(0)
; template <class Epi>
; __device__ __forceinline__ void gemm_phase(LAS unsigned char* lds, const Gemm g, const StaticOrder& S, const Epi& E, int wv) {
;     ...
;     for (;;) {
;         const bool has_next = S.next(ui + 1, nxt);
;         const char* nA = has_next ? (const char*)g.A + (size_t)nxt.pm * tstepA : cA; const char* nB = has_next ? (const char*)g.Bt + (size_t)nxt.pn * tstepB : cB;
;         for (int t = 0; t < nt; t += 2) {
;             const bool last = (t == nt - 2);
;             const char* a1 = cA + (size_t)(t + 1) * kstep;
;             const char* a2 = last ? nA : cA + (size_t)(t + 2) * kstep; const char* b2 = last ? nB : cB + (size_t)(t + 2) * kstep;
;             const char* a3 = a2 + kstep; const char* b3 = b2 + kstep;
;             PG8_LDB(B0, 0, 0); PG8_SCHED; PG8_LDA(At, 0, 0); PG8_STAGE(PG8_SA(1, 1), a1 + hstep, voffA);
;             PG8_WAIT_L(8); PG8_BAR; PG8_WAIT_L(0); PG8_MMA(0, 0, At, B0); PG8_BAR; PG8_SCHED;
;             PG8_LDB(B1, 0, 1); PG8_STAGE(PG8_SB(0, 0), b2, voffB);
;             PG8_BAR; PG8_WAIT_L(0); PG8_MMA(0, 1, At, B1); PG8_BAR;
;     __device__ __forceinline__ void operator()(const f32x4 (&acc)[2][2][4][2], const Unit& u, int wr, int wc, int fr, int fq) const {
;     ...
;             for (int n = 0; n < 2; ++n) gv[bj][n] = *(const f32x4*)(gate + u.pn * 256 + bj * 128 + wc * 32 + n * 16 + 4 * fq);
.LBB0_1121:
	s_add_u32 s38, s38, 0xb0080
	s_addc_u32 s39, s39, 0
	s_add_u32 s37, s40, 0x100
	s_addc_u32 s73, s41, 0
	s_mov_b32 s74, -2
	s_cmp_gt_i32 s36, 63
	s_cselect_b32 s98, s66, 0x1645000
	s_add_u32 s98, s10, s98
	s_addc_u32 s99, s11, 0
	s_lshl_b32 s100, s12, 8
	s_ashr_i32 s101, s100, 31
	s_lshl_b64 s[100:101], s[100:101], 2
	s_add_u32 s98, s98, s100
	s_addc_u32 s99, s99, s101
	s_lshl_b32 s100, s56, 2
	s_add_u32 s98, s98, s100
	s_addc_u32 s99, s99, 0
	v_mbcnt_lo_u32_b32 v240, -1, 0
	v_mbcnt_hi_u32_b32 v240, -1, v240
	v_lshrrev_b32_e32 v240, 2, v240
	v_and_b32_e32 v240, 28, v240
	v_lshlrev_b32_e32 v240, 2, v240
	global_load_dwordx4 v[236:239], v240, s[98:99]
	global_load_dwordx4 v[232:235], v240, s[98:99] offset:64
	global_load_dwordx4 v[228:231], v240, s[98:99] offset:512
	global_load_dwordx4 v[224:227], v240, s[98:99] offset:576
	ds_read_b128 v[128:131], v165
	ds_read_b128 v[132:135], v165 offset:1024
	ds_read_b128 v[136:139], v165 offset:2048
	ds_read_b128 v[140:143], v165 offset:3072
	s_add_u32 s40, s38, 0xfff50080
	s_addc_u32 s41, s39, -1
	s_cmp_eq_u32 s74, 40
	s_cselect_b32 s43, s5, s41
	s_cselect_b32 s42, s4, s40
	s_cselect_b32 s41, s7, s73
	s_cselect_b32 s40, s6, s37
	ds_read_b128 v[168:171], v166
	ds_read_b128 v[172:175], v166 offset:1024
	ds_read_b128 v[176:179], v166 offset:2048
	ds_read_b128 v[180:183], v166 offset:3072
	ds_read_b128 v[184:187], v166 offset:4096
	ds_read_b128 v[188:191], v166 offset:5120
	ds_read_b128 v[192:195], v166 offset:6144
	ds_read_b128 v[196:199], v166 offset:7168
	ds_read_b128 v[200:203], v167
	ds_read_b128 v[204:207], v167 offset:1024
	ds_read_b128 v[208:211], v167 offset:2048
	ds_read_b128 v[212:215], v167 offset:3072
	v_lshl_add_u64 v[252:253], s[38:39], 0, v[154:155]
	s_add_i32 m0, s51, 0xc000
	s_nop 0
	global_load_lds_dwordx4 v[252:253], off
	v_lshl_add_u64 v[252:253], s[38:39], 0, v[156:157]
	s_add_i32 m0, s51, 0xe000
	s_nop 0
	global_load_lds_dwordx4 v[252:253], off
	s_waitcnt vmcnt(8)
	s_waitcnt lgkmcnt(0)
	s_barrier
	s_setprio 1
	v_mfma_f32_16x16x32_bf16 v[124:127], v[128:131], v[168:171], 0
	v_mfma_f32_16x16x32_bf16 v[120:123], v[136:139], v[168:171], 0
	v_mfma_f32_16x16x32_bf16 v[116:119], v[128:131], v[176:179], 0
	v_mfma_f32_16x16x32_bf16 v[112:115], v[136:139], v[176:179], 0
	v_mfma_f32_16x16x32_bf16 v[108:111], v[128:131], v[184:187], 0
	v_mfma_f32_16x16x32_bf16 v[96:99], v[136:139], v[184:187], 0
	v_mfma_f32_16x16x32_bf16 v[80:83], v[128:131], v[192:195], 0
	v_mfma_f32_16x16x32_bf16 v[72:75], v[136:139], v[192:195], 0
	v_mfma_f32_16x16x32_bf16 v[124:127], v[132:135], v[172:175], v[124:127]
	v_mfma_f32_16x16x32_bf16 v[120:123], v[140:143], v[172:175], v[120:123]
	v_mfma_f32_16x16x32_bf16 v[116:119], v[132:135], v[180:183], v[116:119]
	v_mfma_f32_16x16x32_bf16 v[112:115], v[140:143], v[180:183], v[112:115]
	v_mfma_f32_16x16x32_bf16 v[108:111], v[132:135], v[188:191], v[108:111]
	v_mfma_f32_16x16x32_bf16 v[96:99], v[140:143], v[188:191], v[96:99]
	v_mfma_f32_16x16x32_bf16 v[80:83], v[132:135], v[196:199], v[80:83]
	v_mfma_f32_16x16x32_bf16 v[72:75], v[140:143], v[196:199], v[72:75]
	v_mfma_f32_16x16x32_bf16 v[104:107], v[200:203], v[168:171], 0
	v_mfma_f32_16x16x32_bf16 v[100:103], v[208:211], v[168:171], 0
	v_mfma_f32_16x16x32_bf16 v[92:95], v[200:203], v[176:179], 0
	v_mfma_f32_16x16x32_bf16 v[88:91], v[208:211], v[176:179], 0
	v_mfma_f32_16x16x32_bf16 v[84:87], v[200:203], v[184:187], 0
	v_mfma_f32_16x16x32_bf16 v[76:79], v[208:211], v[184:187], 0
	v_mfma_f32_16x16x32_bf16 v[68:71], v[200:203], v[192:195], 0
	v_mfma_f32_16x16x32_bf16 v[64:67], v[208:211], v[192:195], 0
	v_mfma_f32_16x16x32_bf16 v[104:107], v[204:207], v[172:175], v[104:107]
	v_mfma_f32_16x16x32_bf16 v[100:103], v[212:215], v[172:175], v[100:103]
	v_mfma_f32_16x16x32_bf16 v[92:95], v[204:207], v[180:183], v[92:95]
	v_mfma_f32_16x16x32_bf16 v[88:91], v[212:215], v[180:183], v[88:91]
	v_mfma_f32_16x16x32_bf16 v[84:87], v[204:207], v[188:191], v[84:87]
	v_mfma_f32_16x16x32_bf16 v[76:79], v[212:215], v[188:191], v[76:79]
	v_mfma_f32_16x16x32_bf16 v[68:71], v[204:207], v[196:199], v[68:71]
	v_mfma_f32_16x16x32_bf16 v[64:67], v[212:215], v[196:199], v[64:67]
	s_setprio 0
	s_barrier
	ds_read_b128 v[168:171], v166 offset:16384
	ds_read_b128 v[172:175], v166 offset:17408
	ds_read_b128 v[176:179], v166 offset:18432
	ds_read_b128 v[180:183], v166 offset:19456
	ds_read_b128 v[184:187], v166 offset:20480
	ds_read_b128 v[188:191], v166 offset:21504
	ds_read_b128 v[192:195], v166 offset:22528
	ds_read_b128 v[196:199], v166 offset:23552
	s_add_i32 s75, s64, s50
	v_lshl_add_u64 v[162:163], s[40:41], 0, v[146:147]
	s_mov_b32 m0, s75
	s_nop 0
	global_load_lds_dwordx4 v[162:163], off
	v_lshl_add_u64 v[216:217], s[40:41], 0, v[150:151]
	s_add_i32 m0, s75, 0x2000
	s_nop 0
	global_load_lds_dwordx4 v[216:217], off
	s_mov_b32 m0, s51
	v_lshl_add_u64 v[218:219], s[42:43], 0, v[144:145]
	global_load_lds_dwordx4 v[218:219], off
	v_lshl_add_u64 v[220:221], s[42:43], 0, v[148:149]
	s_mov_b32 m0, s52
	s_nop 0
	global_load_lds_dwordx4 v[220:221], off
	s_add_u32 s76, s40, 0xb0000
	s_addc_u32 s77, s41, 0
	s_add_i32 s75, s65, s50
	v_lshl_add_u64 v[254:255], s[76:77], 0, v[146:147]
	s_mov_b32 m0, s75
	s_nop 0
	global_load_lds_dwordx4 v[254:255], off
	v_lshl_add_u64 v[254:255], s[76:77], 0, v[150:151]
	s_add_i32 m0, s75, 0x2000
	s_nop 0
	global_load_lds_dwordx4 v[254:255], off
	s_waitcnt vmcnt(8)
	s_waitcnt lgkmcnt(0)
	s_barrier
; #define PG8_STAGE(bufoff, gbase, voff) do { _Pragma("unroll") for (int _i = 0; _i < 2; ++_i) \
;         __builtin_amdgcn_global_load_lds((const unsigned*)((const char*)(gbase) + (voff)[_i]), (LAS unsigned*)(lds + (bufoff) + ldsw + _i * 8192), 16, 0, 0); } while (0)
; #define PG8_LDA(dst, b, h) do { _Pragma("unroll") for (int m = 0; m < 4; ++m) _Pragma("unroll") for (int k = 0; k < 2; ++k) dst[m][k] = *(const LAS bf16x8*)(lds + PG8_SA(b, h) + aoff + m * 2048 + k * 1024); } while (0)
; #define PG8_LDB(dst, b, h) do { _Pragma("unroll") for (int n = 0; n < 2; ++n) _Pragma("unroll") for (int k = 0; k < 2; ++k) dst[n][k] = *(const LAS bf16x8*)(lds + PG8_SB(b, h) + boff + n * 2048 + k * 1024); } while (0)
; #define PG8_MMA(ai, bj, At, Bt) do { __builtin_amdgcn_s_setprio(1); _Pragma("unroll") for (int m = 0; m < 4; ++m) _Pragma("unroll") for (int n = 0; n < 2; ++n) _Pragma("unroll") for (int k = 0; k < 2; ++k) \
;         acc[ai][bj][m][n] = __builtin_amdgcn_mfma_f32_16x16x32_bf16(Bt[n][k], At[m][k], acc[ai][bj][m][n], 0, 0, 0); __builtin_amdgcn_s_setprio(0); } while (0)
; #define PG8_WAIT_V(n) asm volatile("s_waitcnt vmcnt(" #n ")" ::: "memory")
; #define PG8_WAIT_L(n) asm volatile("s_waitcnt lgkmcnt(" #n ")" ::: "memory")
; #define PG8_BAR __builtin_amdgcn_s_barrier()
; #define PG8_SCHED __builtin_amdgcn_sched_barrier(0)
; template <class Epi>
; __device__ __forceinline__ void gemm_phase(LAS unsigned char* lds, const Gemm g, const StaticOrder& S, const Epi& E, int wv) {
;     ...
;             PG8_LDB(B0, 0, 0); PG8_SCHED; PG8_LDA(At, 0, 0); PG8_STAGE(PG8_SA(1, 1), a1 + hstep, voffA);
;             PG8_WAIT_L(8); PG8_BAR; PG8_WAIT_L(0); PG8_MMA(0, 0, At, B0); PG8_BAR; PG8_SCHED;
;             PG8_LDB(B1, 0, 1); PG8_STAGE(PG8_SB(0, 0), b2, voffB);
;             PG8_BAR; PG8_WAIT_L(0); PG8_MMA(0, 1, At, B1); PG8_BAR;
;             PG8_LDA(At, 0, 1); PG8_STAGE(PG8_SA(0, 0), a2, voffA);
;             PG8_BAR; PG8_WAIT_L(0); PG8_MMA(1, 0, At, B0); PG8_BAR; PG8_SCHED;
;             PG8_STAGE(PG8_SB(0, 1), b2 + hstep, voffB);
;             PG8_WAIT_V(6); PG8_BAR; PG8_MMA(1, 1, At, B1); PG8_BAR;
	s_setprio 1
	v_mfma_f32_16x16x32_bf16 v[60:63], v[128:131], v[168:171], 0
	v_mfma_f32_16x16x32_bf16 v[56:59], v[136:139], v[168:171], 0
	v_mfma_f32_16x16x32_bf16 v[48:51], v[128:131], v[176:179], 0
	v_mfma_f32_16x16x32_bf16 v[40:43], v[136:139], v[176:179], 0
	v_mfma_f32_16x16x32_bf16 v[32:35], v[128:131], v[184:187], 0
	v_mfma_f32_16x16x32_bf16 v[24:27], v[136:139], v[184:187], 0
	v_mfma_f32_16x16x32_bf16 v[16:19], v[128:131], v[192:195], 0
	v_mfma_f32_16x16x32_bf16 v[8:11], v[136:139], v[192:195], 0
	v_mfma_f32_16x16x32_bf16 v[60:63], v[132:135], v[172:175], v[60:63]
	v_mfma_f32_16x16x32_bf16 v[56:59], v[140:143], v[172:175], v[56:59]
	v_mfma_f32_16x16x32_bf16 v[48:51], v[132:135], v[180:183], v[48:51]
	v_mfma_f32_16x16x32_bf16 v[40:43], v[140:143], v[180:183], v[40:43]
	v_mfma_f32_16x16x32_bf16 v[32:35], v[132:135], v[188:191], v[32:35]
	v_mfma_f32_16x16x32_bf16 v[24:27], v[140:143], v[188:191], v[24:27]
	v_mfma_f32_16x16x32_bf16 v[16:19], v[132:135], v[196:199], v[16:19]
	v_mfma_f32_16x16x32_bf16 v[8:11], v[140:143], v[196:199], v[8:11]
	v_mfma_f32_16x16x32_bf16 v[52:55], v[200:203], v[168:171], 0
	v_mfma_f32_16x16x32_bf16 v[44:47], v[208:211], v[168:171], 0
	v_mfma_f32_16x16x32_bf16 v[36:39], v[200:203], v[176:179], 0
	v_mfma_f32_16x16x32_bf16 v[28:31], v[208:211], v[176:179], 0
	v_mfma_f32_16x16x32_bf16 v[20:23], v[200:203], v[184:187], 0
	v_mfma_f32_16x16x32_bf16 v[12:15], v[208:211], v[184:187], 0
	v_mfma_f32_16x16x32_bf16 v[4:7], v[200:203], v[192:195], 0
	v_mfma_f32_16x16x32_bf16 v[0:3], v[208:211], v[192:195], 0
	v_mfma_f32_16x16x32_bf16 v[52:55], v[204:207], v[172:175], v[52:55]
	v_mfma_f32_16x16x32_bf16 v[44:47], v[212:215], v[172:175], v[44:47]
	v_mfma_f32_16x16x32_bf16 v[36:39], v[204:207], v[180:183], v[36:39]
	v_mfma_f32_16x16x32_bf16 v[28:31], v[212:215], v[180:183], v[28:31]
	v_mfma_f32_16x16x32_bf16 v[20:23], v[204:207], v[188:191], v[20:23]
	v_mfma_f32_16x16x32_bf16 v[12:15], v[212:215], v[188:191], v[12:15]
	v_mfma_f32_16x16x32_bf16 v[4:7], v[204:207], v[196:199], v[4:7]
	v_mfma_f32_16x16x32_bf16 v[0:3], v[212:215], v[196:199], v[0:3]
	s_setprio 0
	s_add_i32 s75, 0, 0x18000
	v_add_u32_e32 v140, s75, v164
	s_barrier
	ds_read_b128 v[128:131], v140
	ds_read_b128 v[132:135], v140 offset:1024
	ds_read_b128 v[136:139], v140 offset:2048
	ds_read_b128 v[140:143], v140 offset:3072
	s_add_u32 s42, s42, 0xb0000
	s_addc_u32 s43, s43, 0
	ds_read_b128 v[168:171], v166 offset:32768
	ds_read_b128 v[172:175], v166 offset:33792
	ds_read_b128 v[176:179], v166 offset:34816
	ds_read_b128 v[180:183], v166 offset:35840
	ds_read_b128 v[184:187], v166 offset:36864
	ds_read_b128 v[188:191], v166 offset:37888
	ds_read_b128 v[192:195], v166 offset:38912
	ds_read_b128 v[196:199], v166 offset:39936
	s_mov_b32 m0, s53
	v_lshl_add_u64 v[252:253], s[42:43], 0, v[144:145]
	global_load_lds_dwordx4 v[252:253], off
	v_lshl_add_u64 v[252:253], s[42:43], 0, v[148:149]
	s_mov_b32 m0, s54
	s_nop 0
	global_load_lds_dwordx4 v[252:253], off
	s_add_i32 s42, 0, 0x1c000
	v_add_u32_e32 v152, s42, v164
	ds_read_b128 v[200:203], v152
	ds_read_b128 v[204:207], v152 offset:1024
	ds_read_b128 v[208:211], v152 offset:2048
	ds_read_b128 v[212:215], v152 offset:3072
	s_waitcnt vmcnt(8)
	s_waitcnt lgkmcnt(0)
	s_barrier
	s_setprio 1
	v_mfma_f32_16x16x32_bf16 v[124:127], v[128:131], v[168:171], v[124:127]
	v_mfma_f32_16x16x32_bf16 v[120:123], v[136:139], v[168:171], v[120:123]
	v_mfma_f32_16x16x32_bf16 v[116:119], v[128:131], v[176:179], v[116:119]
	v_mfma_f32_16x16x32_bf16 v[112:115], v[136:139], v[176:179], v[112:115]
	v_mfma_f32_16x16x32_bf16 v[108:111], v[128:131], v[184:187], v[108:111]
	v_mfma_f32_16x16x32_bf16 v[96:99], v[136:139], v[184:187], v[96:99]
	v_mfma_f32_16x16x32_bf16 v[80:83], v[128:131], v[192:195], v[80:83]
	v_mfma_f32_16x16x32_bf16 v[72:75], v[136:139], v[192:195], v[72:75]
	v_mfma_f32_16x16x32_bf16 v[124:127], v[132:135], v[172:175], v[124:127]
	v_mfma_f32_16x16x32_bf16 v[120:123], v[140:143], v[172:175], v[120:123]
	v_mfma_f32_16x16x32_bf16 v[116:119], v[132:135], v[180:183], v[116:119]
	v_mfma_f32_16x16x32_bf16 v[112:115], v[140:143], v[180:183], v[112:115]
	v_mfma_f32_16x16x32_bf16 v[108:111], v[132:135], v[188:191], v[108:111]
	v_mfma_f32_16x16x32_bf16 v[96:99], v[140:143], v[188:191], v[96:99]
	v_mfma_f32_16x16x32_bf16 v[80:83], v[132:135], v[196:199], v[80:83]
	v_mfma_f32_16x16x32_bf16 v[72:75], v[140:143], v[196:199], v[72:75]
	v_mfma_f32_16x16x32_bf16 v[104:107], v[200:203], v[168:171], v[104:107]
	v_mfma_f32_16x16x32_bf16 v[100:103], v[208:211], v[168:171], v[100:103]
	v_mfma_f32_16x16x32_bf16 v[92:95], v[200:203], v[176:179], v[92:95]
	v_mfma_f32_16x16x32_bf16 v[88:91], v[208:211], v[176:179], v[88:91]
	v_mfma_f32_16x16x32_bf16 v[84:87], v[200:203], v[184:187], v[84:87]
	v_mfma_f32_16x16x32_bf16 v[76:79], v[208:211], v[184:187], v[76:79]
	v_mfma_f32_16x16x32_bf16 v[68:71], v[200:203], v[192:195], v[68:71]
	v_mfma_f32_16x16x32_bf16 v[64:67], v[208:211], v[192:195], v[64:67]
	v_mfma_f32_16x16x32_bf16 v[104:107], v[204:207], v[172:175], v[104:107]
	v_mfma_f32_16x16x32_bf16 v[100:103], v[212:215], v[172:175], v[100:103]
	v_mfma_f32_16x16x32_bf16 v[92:95], v[204:207], v[180:183], v[92:95]
	v_mfma_f32_16x16x32_bf16 v[88:91], v[212:215], v[180:183], v[88:91]
	v_mfma_f32_16x16x32_bf16 v[84:87], v[204:207], v[188:191], v[84:87]
	v_mfma_f32_16x16x32_bf16 v[76:79], v[212:215], v[188:191], v[76:79]
	v_mfma_f32_16x16x32_bf16 v[68:71], v[204:207], v[196:199], v[68:71]
	v_mfma_f32_16x16x32_bf16 v[64:67], v[212:215], v[196:199], v[64:67]
	s_setprio 0
	s_barrier
; #define PG8_STAGE(bufoff, gbase, voff) do { _Pragma("unroll") for (int _i = 0; _i < 2; ++_i) \
;         __builtin_amdgcn_global_load_lds((const unsigned*)((const char*)(gbase) + (voff)[_i]), (LAS unsigned*)(lds + (bufoff) + ldsw + _i * 8192), 16, 0, 0); } while (0)
; #define PG8_LDA(dst, b, h) do { _Pragma("unroll") for (int m = 0; m < 4; ++m) _Pragma("unroll") for (int k = 0; k < 2; ++k) dst[m][k] = *(const LAS bf16x8*)(lds + PG8_SA(b, h) + aoff + m * 2048 + k * 1024); } while (0)
; #define PG8_LDB(dst, b, h) do { _Pragma("unroll") for (int n = 0; n < 2; ++n) _Pragma("unroll") for (int k = 0; k < 2; ++k) dst[n][k] = *(const LAS bf16x8*)(lds + PG8_SB(b, h) + boff + n * 2048 + k * 1024); } while (0)
; #define PG8_MMA(ai, bj, At, Bt) do { __builtin_amdgcn_s_setprio(1); _Pragma("unroll") for (int m = 0; m < 4; ++m) _Pragma("unroll") for (int n = 0; n < 2; ++n) _Pragma("unroll") for (int k = 0; k < 2; ++k) \
;         acc[ai][bj][m][n] = __builtin_amdgcn_mfma_f32_16x16x32_bf16(Bt[n][k], At[m][k], acc[ai][bj][m][n], 0, 0, 0); __builtin_amdgcn_s_setprio(0); } while (0)
; #define PG8_BAR __builtin_amdgcn_s_barrier()
; template <class Epi>
; __device__ __forceinline__ void gemm_phase(LAS unsigned char* lds, const Gemm g, const StaticOrder& S, const Epi& E, int wv) {
;     ...
;         for (int t = 0; t < nt; t += 2) {
;             const bool last = (t == nt - 2);
;             const char* a1 = cA + (size_t)(t + 1) * kstep;
;             const char* a2 = last ? nA : cA + (size_t)(t + 2) * kstep; const char* b2 = last ? nB : cB + (size_t)(t + 2) * kstep;
;             const char* a3 = a2 + kstep; const char* b3 = b2 + kstep;
;             PG8_LDB(B0, 0, 0); PG8_SCHED; PG8_LDA(At, 0, 0); PG8_STAGE(PG8_SA(1, 1), a1 + hstep, voffA);
;     ...
;             PG8_LDB(B0, 1, 0); PG8_SCHED; PG8_LDA(At, 1, 0); PG8_STAGE(PG8_SA(0, 1), a2 + hstep, voffA);
;             PG8_WAIT_L(8); PG8_BAR; PG8_WAIT_L(0); PG8_MMA(0, 0, At, B0); PG8_BAR; PG8_SCHED;
;             PG8_LDB(B1, 1, 1); PG8_STAGE(PG8_SB(1, 0), b3, voffB);
;             PG8_BAR; PG8_WAIT_L(0); PG8_MMA(0, 1, At, B1); PG8_BAR;
;             PG8_LDA(At, 1, 1); PG8_STAGE(PG8_SA(1, 0), a3, voffA);
;             PG8_BAR; PG8_WAIT_L(0); PG8_MMA(1, 0, At, B0); PG8_BAR; PG8_SCHED;
;             PG8_STAGE(PG8_SB(1, 1), b3 + hstep, voffB);
;             PG8_WAIT_V(6); PG8_BAR; PG8_MMA(1, 1, At, B1); PG8_BAR;
;         }
	ds_read_b128 v[168:171], v166 offset:49152
	ds_read_b128 v[172:175], v166 offset:50176
	ds_read_b128 v[176:179], v166 offset:51200
	ds_read_b128 v[180:183], v166 offset:52224
	ds_read_b128 v[184:187], v166 offset:53248
	ds_read_b128 v[188:191], v166 offset:54272
	ds_read_b128 v[192:195], v166 offset:55296
	ds_read_b128 v[196:199], v166 offset:56320
	s_add_i32 s43, s75, s50
	v_lshl_add_u64 v[162:163], v[162:163], 0, s[16:17]
	s_mov_b32 m0, s43
	s_nop 0
	global_load_lds_dwordx4 v[162:163], off
	v_lshl_add_u64 v[162:163], v[216:217], 0, s[16:17]
	s_add_i32 m0, s43, 0x2000
	s_nop 0
	global_load_lds_dwordx4 v[162:163], off
	s_mov_b32 m0, s57
	v_lshl_add_u64 v[162:163], v[218:219], 0, s[16:17]
	global_load_lds_dwordx4 v[162:163], off
	v_lshl_add_u64 v[162:163], v[220:221], 0, s[16:17]
	s_mov_b32 m0, s58
	s_nop 0
	global_load_lds_dwordx4 v[162:163], off
	s_add_u32 s40, s40, 0xb0080
	s_addc_u32 s41, s41, 0
	s_add_i32 s42, s42, s50
	v_lshl_add_u64 v[254:255], s[40:41], 0, v[146:147]
	s_mov_b32 m0, s42
	s_nop 0
	global_load_lds_dwordx4 v[254:255], off
	v_lshl_add_u64 v[254:255], s[40:41], 0, v[150:151]
	s_add_i32 m0, s42, 0x2000
	s_nop 0
	global_load_lds_dwordx4 v[254:255], off
	s_waitcnt vmcnt(8)
	s_waitcnt lgkmcnt(0)
	s_barrier
	s_setprio 1
	v_mfma_f32_16x16x32_bf16 v[60:63], v[128:131], v[168:171], v[60:63]
	v_mfma_f32_16x16x32_bf16 v[56:59], v[136:139], v[168:171], v[56:59]
	v_mfma_f32_16x16x32_bf16 v[48:51], v[128:131], v[176:179], v[48:51]
	v_mfma_f32_16x16x32_bf16 v[40:43], v[136:139], v[176:179], v[40:43]
	v_mfma_f32_16x16x32_bf16 v[32:35], v[128:131], v[184:187], v[32:35]
	v_mfma_f32_16x16x32_bf16 v[24:27], v[136:139], v[184:187], v[24:27]
	v_mfma_f32_16x16x32_bf16 v[16:19], v[128:131], v[192:195], v[16:19]
	v_mfma_f32_16x16x32_bf16 v[8:11], v[136:139], v[192:195], v[8:11]
	v_mfma_f32_16x16x32_bf16 v[60:63], v[132:135], v[172:175], v[60:63]
	v_mfma_f32_16x16x32_bf16 v[56:59], v[140:143], v[172:175], v[56:59]
	v_mfma_f32_16x16x32_bf16 v[48:51], v[132:135], v[180:183], v[48:51]
	v_mfma_f32_16x16x32_bf16 v[40:43], v[140:143], v[180:183], v[40:43]
	v_mfma_f32_16x16x32_bf16 v[32:35], v[132:135], v[188:191], v[32:35]
	v_mfma_f32_16x16x32_bf16 v[24:27], v[140:143], v[188:191], v[24:27]
	v_mfma_f32_16x16x32_bf16 v[16:19], v[132:135], v[196:199], v[16:19]
	v_mfma_f32_16x16x32_bf16 v[8:11], v[140:143], v[196:199], v[8:11]
	v_mfma_f32_16x16x32_bf16 v[52:55], v[200:203], v[168:171], v[52:55]
	v_mfma_f32_16x16x32_bf16 v[44:47], v[208:211], v[168:171], v[44:47]
	v_mfma_f32_16x16x32_bf16 v[36:39], v[200:203], v[176:179], v[36:39]
	v_mfma_f32_16x16x32_bf16 v[28:31], v[208:211], v[176:179], v[28:31]
	v_mfma_f32_16x16x32_bf16 v[20:23], v[200:203], v[184:187], v[20:23]
	v_mfma_f32_16x16x32_bf16 v[12:15], v[208:211], v[184:187], v[12:15]
	v_mfma_f32_16x16x32_bf16 v[4:7], v[200:203], v[192:195], v[4:7]
	v_mfma_f32_16x16x32_bf16 v[0:3], v[208:211], v[192:195], v[0:3]
	v_mfma_f32_16x16x32_bf16 v[52:55], v[204:207], v[172:175], v[52:55]
	v_mfma_f32_16x16x32_bf16 v[44:47], v[212:215], v[172:175], v[44:47]
	v_mfma_f32_16x16x32_bf16 v[36:39], v[204:207], v[180:183], v[36:39]
	v_mfma_f32_16x16x32_bf16 v[28:31], v[212:215], v[180:183], v[28:31]
	v_mfma_f32_16x16x32_bf16 v[20:23], v[204:207], v[188:191], v[20:23]
	v_mfma_f32_16x16x32_bf16 v[12:15], v[212:215], v[188:191], v[12:15]
	v_mfma_f32_16x16x32_bf16 v[4:7], v[204:207], v[196:199], v[4:7]
	v_mfma_f32_16x16x32_bf16 v[0:3], v[212:215], v[196:199], v[0:3]
	s_setprio 0
	s_add_i32 s74, s74, 2
	s_add_u32 s38, s38, 0x100
	s_addc_u32 s39, s39, 0
	s_add_u32 s37, s37, 0x100
	s_addc_u32 s73, s73, 0
	s_cmp_gt_u32 s74, 41
	s_barrier
.LBB0_1122:
	ds_read_b128 v[128:131], v165
	ds_read_b128 v[132:135], v165 offset:1024
	ds_read_b128 v[136:139], v165 offset:2048
	ds_read_b128 v[140:143], v165 offset:3072
	s_add_u32 s40, s38, 0xfff50080
	s_addc_u32 s41, s39, -1
	s_cmp_eq_u32 s74, 40
	s_cselect_b32 s43, s5, s41
	s_cselect_b32 s42, s4, s40
	s_cselect_b32 s41, s7, s73
	s_cselect_b32 s40, s6, s37
	ds_read_b128 v[168:171], v166
	ds_read_b128 v[172:175], v166 offset:1024
	ds_read_b128 v[176:179], v166 offset:2048
	ds_read_b128 v[180:183], v166 offset:3072
	ds_read_b128 v[184:187], v166 offset:4096
	ds_read_b128 v[188:191], v166 offset:5120
	ds_read_b128 v[192:195], v166 offset:6144
	ds_read_b128 v[196:199], v166 offset:7168
	ds_read_b128 v[200:203], v167
	ds_read_b128 v[204:207], v167 offset:1024
	ds_read_b128 v[208:211], v167 offset:2048
	ds_read_b128 v[212:215], v167 offset:3072
	v_lshl_add_u64 v[252:253], s[38:39], 0, v[154:155]
	s_add_i32 m0, s51, 0xc000
	s_nop 0
	global_load_lds_dwordx4 v[252:253], off
	v_lshl_add_u64 v[252:253], s[38:39], 0, v[156:157]
	s_add_i32 m0, s51, 0xe000
	s_nop 0
	global_load_lds_dwordx4 v[252:253], off
	s_waitcnt vmcnt(8)
	s_waitcnt lgkmcnt(0)
	s_barrier
; #define PG8_STAGE(bufoff, gbase, voff) do { _Pragma("unroll") for (int _i = 0; _i < 2; ++_i) \
;         __builtin_amdgcn_global_load_lds((const unsigned*)((const char*)(gbase) + (voff)[_i]), (LAS unsigned*)(lds + (bufoff) + ldsw + _i * 8192), 16, 0, 0); } while (0)
; #define PG8_LDA(dst, b, h) do { _Pragma("unroll") for (int m = 0; m < 4; ++m) _Pragma("unroll") for (int k = 0; k < 2; ++k) dst[m][k] = *(const LAS bf16x8*)(lds + PG8_SA(b, h) + aoff + m * 2048 + k * 1024); } while (0)
; #define PG8_LDB(dst, b, h) do { _Pragma("unroll") for (int n = 0; n < 2; ++n) _Pragma("unroll") for (int k = 0; k < 2; ++k) dst[n][k] = *(const LAS bf16x8*)(lds + PG8_SB(b, h) + boff + n * 2048 + k * 1024); } while (0)
; #define PG8_MMA(ai, bj, At, Bt) do { __builtin_amdgcn_s_setprio(1); _Pragma("unroll") for (int m = 0; m < 4; ++m) _Pragma("unroll") for (int n = 0; n < 2; ++n) _Pragma("unroll") for (int k = 0; k < 2; ++k) \
;         acc[ai][bj][m][n] = __builtin_amdgcn_mfma_f32_16x16x32_bf16(Bt[n][k], At[m][k], acc[ai][bj][m][n], 0, 0, 0); __builtin_amdgcn_s_setprio(0); } while (0)
; #define PG8_WAIT_V(n) asm volatile("s_waitcnt vmcnt(" #n ")" ::: "memory")
; #define PG8_WAIT_L(n) asm volatile("s_waitcnt lgkmcnt(" #n ")" ::: "memory")
; #define PG8_BAR __builtin_amdgcn_s_barrier()
; #define PG8_SCHED __builtin_amdgcn_sched_barrier(0)
; template <class Epi>
; __device__ __forceinline__ void gemm_phase(LAS unsigned char* lds, const Gemm g, const StaticOrder& S, const Epi& E, int wv) {
;     ...
;             PG8_LDB(B0, 0, 0); PG8_SCHED; PG8_LDA(At, 0, 0); PG8_STAGE(PG8_SA(1, 1), a1 + hstep, voffA);
;             PG8_WAIT_L(8); PG8_BAR; PG8_WAIT_L(0); PG8_MMA(0, 0, At, B0); PG8_BAR; PG8_SCHED;
;             PG8_LDB(B1, 0, 1); PG8_STAGE(PG8_SB(0, 0), b2, voffB);
;             PG8_BAR; PG8_WAIT_L(0); PG8_MMA(0, 1, At, B1); PG8_BAR;
;             PG8_LDA(At, 0, 1); PG8_STAGE(PG8_SA(0, 0), a2, voffA);
;             PG8_BAR; PG8_WAIT_L(0); PG8_MMA(1, 0, At, B0); PG8_BAR; PG8_SCHED;
;             PG8_STAGE(PG8_SB(0, 1), b2 + hstep, voffB);
;             PG8_WAIT_V(6); PG8_BAR; PG8_MMA(1, 1, At, B1); PG8_BAR;
	s_setprio 1
	v_mfma_f32_16x16x32_bf16 v[124:127], v[128:131], v[168:171], v[124:127]
	v_mfma_f32_16x16x32_bf16 v[120:123], v[136:139], v[168:171], v[120:123]
	v_mfma_f32_16x16x32_bf16 v[116:119], v[128:131], v[176:179], v[116:119]
	v_mfma_f32_16x16x32_bf16 v[112:115], v[136:139], v[176:179], v[112:115]
	v_mfma_f32_16x16x32_bf16 v[108:111], v[128:131], v[184:187], v[108:111]
	v_mfma_f32_16x16x32_bf16 v[96:99], v[136:139], v[184:187], v[96:99]
	v_mfma_f32_16x16x32_bf16 v[80:83], v[128:131], v[192:195], v[80:83]
	v_mfma_f32_16x16x32_bf16 v[72:75], v[136:139], v[192:195], v[72:75]
	v_mfma_f32_16x16x32_bf16 v[124:127], v[132:135], v[172:175], v[124:127]
	v_mfma_f32_16x16x32_bf16 v[120:123], v[140:143], v[172:175], v[120:123]
	v_mfma_f32_16x16x32_bf16 v[116:119], v[132:135], v[180:183], v[116:119]
	v_mfma_f32_16x16x32_bf16 v[112:115], v[140:143], v[180:183], v[112:115]
	v_mfma_f32_16x16x32_bf16 v[108:111], v[132:135], v[188:191], v[108:111]
	v_mfma_f32_16x16x32_bf16 v[96:99], v[140:143], v[188:191], v[96:99]
	v_mfma_f32_16x16x32_bf16 v[80:83], v[132:135], v[196:199], v[80:83]
	v_mfma_f32_16x16x32_bf16 v[72:75], v[140:143], v[196:199], v[72:75]
	v_mfma_f32_16x16x32_bf16 v[104:107], v[200:203], v[168:171], v[104:107]
	v_mfma_f32_16x16x32_bf16 v[100:103], v[208:211], v[168:171], v[100:103]
	v_mfma_f32_16x16x32_bf16 v[92:95], v[200:203], v[176:179], v[92:95]
	v_mfma_f32_16x16x32_bf16 v[88:91], v[208:211], v[176:179], v[88:91]
	v_mfma_f32_16x16x32_bf16 v[84:87], v[200:203], v[184:187], v[84:87]
	v_mfma_f32_16x16x32_bf16 v[76:79], v[208:211], v[184:187], v[76:79]
	v_mfma_f32_16x16x32_bf16 v[68:71], v[200:203], v[192:195], v[68:71]
	v_mfma_f32_16x16x32_bf16 v[64:67], v[208:211], v[192:195], v[64:67]
	v_mfma_f32_16x16x32_bf16 v[104:107], v[204:207], v[172:175], v[104:107]
	v_mfma_f32_16x16x32_bf16 v[100:103], v[212:215], v[172:175], v[100:103]
	v_mfma_f32_16x16x32_bf16 v[92:95], v[204:207], v[180:183], v[92:95]
	v_mfma_f32_16x16x32_bf16 v[88:91], v[212:215], v[180:183], v[88:91]
	v_mfma_f32_16x16x32_bf16 v[84:87], v[204:207], v[188:191], v[84:87]
	v_mfma_f32_16x16x32_bf16 v[76:79], v[212:215], v[188:191], v[76:79]
	v_mfma_f32_16x16x32_bf16 v[68:71], v[204:207], v[196:199], v[68:71]
	v_mfma_f32_16x16x32_bf16 v[64:67], v[212:215], v[196:199], v[64:67]
	s_setprio 0
	s_barrier
	ds_read_b128 v[168:171], v166 offset:16384
	ds_read_b128 v[172:175], v166 offset:17408
	ds_read_b128 v[176:179], v166 offset:18432
	ds_read_b128 v[180:183], v166 offset:19456
	ds_read_b128 v[184:187], v166 offset:20480
	ds_read_b128 v[188:191], v166 offset:21504
	ds_read_b128 v[192:195], v166 offset:22528
	ds_read_b128 v[196:199], v166 offset:23552
	s_add_i32 s75, s64, s50
	v_lshl_add_u64 v[162:163], s[40:41], 0, v[146:147]
	s_mov_b32 m0, s75
	s_nop 0
	global_load_lds_dwordx4 v[162:163], off
	v_lshl_add_u64 v[216:217], s[40:41], 0, v[150:151]
	s_add_i32 m0, s75, 0x2000
	s_nop 0
	global_load_lds_dwordx4 v[216:217], off
	s_mov_b32 m0, s51
	v_lshl_add_u64 v[218:219], s[42:43], 0, v[144:145]
	global_load_lds_dwordx4 v[218:219], off
	v_lshl_add_u64 v[220:221], s[42:43], 0, v[148:149]
	s_mov_b32 m0, s52
	s_nop 0
	global_load_lds_dwordx4 v[220:221], off
	s_add_u32 s76, s40, 0xb0000
	s_addc_u32 s77, s41, 0
	s_add_i32 s75, s65, s50
	v_lshl_add_u64 v[254:255], s[76:77], 0, v[146:147]
	s_mov_b32 m0, s75
	s_nop 0
	global_load_lds_dwordx4 v[254:255], off
	v_lshl_add_u64 v[254:255], s[76:77], 0, v[150:151]
	s_add_i32 m0, s75, 0x2000
	s_nop 0
	global_load_lds_dwordx4 v[254:255], off
	s_waitcnt vmcnt(8)
	s_waitcnt lgkmcnt(0)
	s_barrier
	s_setprio 1
	v_mfma_f32_16x16x32_bf16 v[60:63], v[128:131], v[168:171], v[60:63]
	v_mfma_f32_16x16x32_bf16 v[56:59], v[136:139], v[168:171], v[56:59]
	v_mfma_f32_16x16x32_bf16 v[48:51], v[128:131], v[176:179], v[48:51]
	v_mfma_f32_16x16x32_bf16 v[40:43], v[136:139], v[176:179], v[40:43]
	v_mfma_f32_16x16x32_bf16 v[32:35], v[128:131], v[184:187], v[32:35]
	v_mfma_f32_16x16x32_bf16 v[24:27], v[136:139], v[184:187], v[24:27]
	v_mfma_f32_16x16x32_bf16 v[16:19], v[128:131], v[192:195], v[16:19]
	v_mfma_f32_16x16x32_bf16 v[8:11], v[136:139], v[192:195], v[8:11]
	v_mfma_f32_16x16x32_bf16 v[60:63], v[132:135], v[172:175], v[60:63]
	v_mfma_f32_16x16x32_bf16 v[56:59], v[140:143], v[172:175], v[56:59]
	v_mfma_f32_16x16x32_bf16 v[48:51], v[132:135], v[180:183], v[48:51]
	v_mfma_f32_16x16x32_bf16 v[40:43], v[140:143], v[180:183], v[40:43]
	v_mfma_f32_16x16x32_bf16 v[32:35], v[132:135], v[188:191], v[32:35]
	v_mfma_f32_16x16x32_bf16 v[24:27], v[140:143], v[188:191], v[24:27]
	v_mfma_f32_16x16x32_bf16 v[16:19], v[132:135], v[196:199], v[16:19]
	v_mfma_f32_16x16x32_bf16 v[8:11], v[140:143], v[196:199], v[8:11]
	v_mfma_f32_16x16x32_bf16 v[52:55], v[200:203], v[168:171], v[52:55]
	v_mfma_f32_16x16x32_bf16 v[44:47], v[208:211], v[168:171], v[44:47]
	v_mfma_f32_16x16x32_bf16 v[36:39], v[200:203], v[176:179], v[36:39]
	v_mfma_f32_16x16x32_bf16 v[28:31], v[208:211], v[176:179], v[28:31]
	v_mfma_f32_16x16x32_bf16 v[20:23], v[200:203], v[184:187], v[20:23]
	v_mfma_f32_16x16x32_bf16 v[12:15], v[208:211], v[184:187], v[12:15]
	v_mfma_f32_16x16x32_bf16 v[4:7], v[200:203], v[192:195], v[4:7]
	v_mfma_f32_16x16x32_bf16 v[0:3], v[208:211], v[192:195], v[0:3]
	v_mfma_f32_16x16x32_bf16 v[52:55], v[204:207], v[172:175], v[52:55]
	v_mfma_f32_16x16x32_bf16 v[44:47], v[212:215], v[172:175], v[44:47]
	v_mfma_f32_16x16x32_bf16 v[36:39], v[204:207], v[180:183], v[36:39]
	v_mfma_f32_16x16x32_bf16 v[28:31], v[212:215], v[180:183], v[28:31]
	v_mfma_f32_16x16x32_bf16 v[20:23], v[204:207], v[188:191], v[20:23]
	v_mfma_f32_16x16x32_bf16 v[12:15], v[212:215], v[188:191], v[12:15]
	v_mfma_f32_16x16x32_bf16 v[4:7], v[204:207], v[196:199], v[4:7]
	v_mfma_f32_16x16x32_bf16 v[0:3], v[212:215], v[196:199], v[0:3]
	s_setprio 0
	s_add_i32 s75, 0, 0x18000
	v_add_u32_e32 v140, s75, v164
	s_barrier
; #define PG8_STAGE(bufoff, gbase, voff) do { _Pragma("unroll") for (int _i = 0; _i < 2; ++_i) \
;         __builtin_amdgcn_global_load_lds((const unsigned*)((const char*)(gbase) + (voff)[_i]), (LAS unsigned*)(lds + (bufoff) + ldsw + _i * 8192), 16, 0, 0); } while (0)
; #define PG8_LDA(dst, b, h) do { _Pragma("unroll") for (int m = 0; m < 4; ++m) _Pragma("unroll") for (int k = 0; k < 2; ++k) dst[m][k] = *(const LAS bf16x8*)(lds + PG8_SA(b, h) + aoff + m * 2048 + k * 1024); } while (0)
; #define PG8_LDB(dst, b, h) do { _Pragma("unroll") for (int n = 0; n < 2; ++n) _Pragma("unroll") for (int k = 0; k < 2; ++k) dst[n][k] = *(const LAS bf16x8*)(lds + PG8_SB(b, h) + boff + n * 2048 + k * 1024); } while (0)
; #define PG8_MMA(ai, bj, At, Bt) do { __builtin_amdgcn_s_setprio(1); _Pragma("unroll") for (int m = 0; m < 4; ++m) _Pragma("unroll") for (int n = 0; n < 2; ++n) _Pragma("unroll") for (int k = 0; k < 2; ++k) \
;         acc[ai][bj][m][n] = __builtin_amdgcn_mfma_f32_16x16x32_bf16(Bt[n][k], At[m][k], acc[ai][bj][m][n], 0, 0, 0); __builtin_amdgcn_s_setprio(0); } while (0)
; #define PG8_WAIT_L(n) asm volatile("s_waitcnt lgkmcnt(" #n ")" ::: "memory")
; #define PG8_BAR __builtin_amdgcn_s_barrier()
; #define PG8_SCHED __builtin_amdgcn_sched_barrier(0)
; template <class Epi>
; __device__ __forceinline__ void gemm_phase(LAS unsigned char* lds, const Gemm g, const StaticOrder& S, const Epi& E, int wv) {
;     ...
;             PG8_LDB(B0, 1, 0); PG8_SCHED; PG8_LDA(At, 1, 0); PG8_STAGE(PG8_SA(0, 1), a2 + hstep, voffA);
;             PG8_WAIT_L(8); PG8_BAR; PG8_WAIT_L(0); PG8_MMA(0, 0, At, B0); PG8_BAR; PG8_SCHED;
;             PG8_LDB(B1, 1, 1); PG8_STAGE(PG8_SB(1, 0), b3, voffB);
;             PG8_BAR; PG8_WAIT_L(0); PG8_MMA(0, 1, At, B1); PG8_BAR;
;             PG8_LDA(At, 1, 1); PG8_STAGE(PG8_SA(1, 0), a3, voffA);
;             PG8_BAR; PG8_WAIT_L(0); PG8_MMA(1, 0, At, B0); PG8_BAR; PG8_SCHED;
	ds_read_b128 v[128:131], v140
	ds_read_b128 v[132:135], v140 offset:1024
	ds_read_b128 v[136:139], v140 offset:2048
	ds_read_b128 v[140:143], v140 offset:3072
	s_add_u32 s42, s42, 0xb0000
	s_addc_u32 s43, s43, 0
	ds_read_b128 v[168:171], v166 offset:32768
	ds_read_b128 v[172:175], v166 offset:33792
	ds_read_b128 v[176:179], v166 offset:34816
	ds_read_b128 v[180:183], v166 offset:35840
	ds_read_b128 v[184:187], v166 offset:36864
	ds_read_b128 v[188:191], v166 offset:37888
	ds_read_b128 v[192:195], v166 offset:38912
	ds_read_b128 v[196:199], v166 offset:39936
	s_mov_b32 m0, s53
	v_lshl_add_u64 v[252:253], s[42:43], 0, v[144:145]
	global_load_lds_dwordx4 v[252:253], off
	v_lshl_add_u64 v[252:253], s[42:43], 0, v[148:149]
	s_mov_b32 m0, s54
	s_nop 0
	global_load_lds_dwordx4 v[252:253], off
	s_add_i32 s42, 0, 0x1c000
	v_add_u32_e32 v152, s42, v164
	ds_read_b128 v[200:203], v152
	ds_read_b128 v[204:207], v152 offset:1024
	ds_read_b128 v[208:211], v152 offset:2048
	ds_read_b128 v[212:215], v152 offset:3072
	s_waitcnt vmcnt(8)
	s_waitcnt lgkmcnt(0)
	s_barrier
	s_setprio 1
	v_mfma_f32_16x16x32_bf16 v[124:127], v[128:131], v[168:171], v[124:127]
	v_mfma_f32_16x16x32_bf16 v[120:123], v[136:139], v[168:171], v[120:123]
	v_mfma_f32_16x16x32_bf16 v[116:119], v[128:131], v[176:179], v[116:119]
	v_mfma_f32_16x16x32_bf16 v[112:115], v[136:139], v[176:179], v[112:115]
	v_mfma_f32_16x16x32_bf16 v[108:111], v[128:131], v[184:187], v[108:111]
	v_mfma_f32_16x16x32_bf16 v[96:99], v[136:139], v[184:187], v[96:99]
	v_mfma_f32_16x16x32_bf16 v[80:83], v[128:131], v[192:195], v[80:83]
	v_mfma_f32_16x16x32_bf16 v[72:75], v[136:139], v[192:195], v[72:75]
	v_mfma_f32_16x16x32_bf16 v[124:127], v[132:135], v[172:175], v[124:127]
	v_mfma_f32_16x16x32_bf16 v[120:123], v[140:143], v[172:175], v[120:123]
	v_mfma_f32_16x16x32_bf16 v[116:119], v[132:135], v[180:183], v[116:119]
	v_mfma_f32_16x16x32_bf16 v[112:115], v[140:143], v[180:183], v[112:115]
	v_mfma_f32_16x16x32_bf16 v[108:111], v[132:135], v[188:191], v[108:111]
	v_mfma_f32_16x16x32_bf16 v[96:99], v[140:143], v[188:191], v[96:99]
	v_mfma_f32_16x16x32_bf16 v[80:83], v[132:135], v[196:199], v[80:83]
	v_mfma_f32_16x16x32_bf16 v[72:75], v[140:143], v[196:199], v[72:75]
	v_mfma_f32_16x16x32_bf16 v[104:107], v[200:203], v[168:171], v[104:107]
	v_mfma_f32_16x16x32_bf16 v[100:103], v[208:211], v[168:171], v[100:103]
	v_mfma_f32_16x16x32_bf16 v[92:95], v[200:203], v[176:179], v[92:95]
	v_mfma_f32_16x16x32_bf16 v[88:91], v[208:211], v[176:179], v[88:91]
	v_mfma_f32_16x16x32_bf16 v[84:87], v[200:203], v[184:187], v[84:87]
	v_mfma_f32_16x16x32_bf16 v[76:79], v[208:211], v[184:187], v[76:79]
	v_mfma_f32_16x16x32_bf16 v[68:71], v[200:203], v[192:195], v[68:71]
	v_mfma_f32_16x16x32_bf16 v[64:67], v[208:211], v[192:195], v[64:67]
	v_mfma_f32_16x16x32_bf16 v[104:107], v[204:207], v[172:175], v[104:107]
	v_mfma_f32_16x16x32_bf16 v[100:103], v[212:215], v[172:175], v[100:103]
	v_mfma_f32_16x16x32_bf16 v[92:95], v[204:207], v[180:183], v[92:95]
	v_mfma_f32_16x16x32_bf16 v[88:91], v[212:215], v[180:183], v[88:91]
	v_mfma_f32_16x16x32_bf16 v[84:87], v[204:207], v[188:191], v[84:87]
	v_mfma_f32_16x16x32_bf16 v[76:79], v[212:215], v[188:191], v[76:79]
	v_mfma_f32_16x16x32_bf16 v[68:71], v[204:207], v[196:199], v[68:71]
	v_mfma_f32_16x16x32_bf16 v[64:67], v[212:215], v[196:199], v[64:67]
	s_setprio 0
	s_barrier
	ds_read_b128 v[168:171], v166 offset:49152
	ds_read_b128 v[172:175], v166 offset:50176
	ds_read_b128 v[176:179], v166 offset:51200
	ds_read_b128 v[180:183], v166 offset:52224
	ds_read_b128 v[184:187], v166 offset:53248
	ds_read_b128 v[188:191], v166 offset:54272
	ds_read_b128 v[192:195], v166 offset:55296
	ds_read_b128 v[196:199], v166 offset:56320
	s_add_i32 s43, s75, s50
	v_lshl_add_u64 v[162:163], v[162:163], 0, s[16:17]
	s_mov_b32 m0, s43
	s_nop 0
	global_load_lds_dwordx4 v[162:163], off
	v_lshl_add_u64 v[162:163], v[216:217], 0, s[16:17]
	s_add_i32 m0, s43, 0x2000
	s_nop 0
	global_load_lds_dwordx4 v[162:163], off
	s_mov_b32 m0, s57
	v_lshl_add_u64 v[162:163], v[218:219], 0, s[16:17]
	global_load_lds_dwordx4 v[162:163], off
	v_lshl_add_u64 v[162:163], v[220:221], 0, s[16:17]
	s_mov_b32 m0, s58
	s_nop 0
	global_load_lds_dwordx4 v[162:163], off
	s_add_u32 s40, s40, 0xb0080
	s_addc_u32 s41, s41, 0
	s_add_i32 s42, s42, s50
	v_lshl_add_u64 v[254:255], s[40:41], 0, v[146:147]
	s_mov_b32 m0, s42
	s_nop 0
	global_load_lds_dwordx4 v[254:255], off
	v_lshl_add_u64 v[254:255], s[40:41], 0, v[150:151]
	s_add_i32 m0, s42, 0x2000
	s_nop 0
	global_load_lds_dwordx4 v[254:255], off
	s_waitcnt vmcnt(8)
	s_waitcnt lgkmcnt(0)
	s_barrier
; __device__ __forceinline__ unsigned pk2(float lo, float hi) { unsigned r; asm("v_cvt_pk_bf16_f32 %0, %1, %2" : "=v"(r) : "v"(lo), "v"(hi)); return r; }
; #define PG8_STAGE(bufoff, gbase, voff) do { _Pragma("unroll") for (int _i = 0; _i < 2; ++_i) \
;         __builtin_amdgcn_global_load_lds((const unsigned*)((const char*)(gbase) + (voff)[_i]), (LAS unsigned*)(lds + (bufoff) + ldsw + _i * 8192), 16, 0, 0); } while (0)
; #define PG8_MMA(ai, bj, At, Bt) do { __builtin_amdgcn_s_setprio(1); _Pragma("unroll") for (int m = 0; m < 4; ++m) _Pragma("unroll") for (int n = 0; n < 2; ++n) _Pragma("unroll") for (int k = 0; k < 2; ++k) \
;         acc[ai][bj][m][n] = __builtin_amdgcn_mfma_f32_16x16x32_bf16(Bt[n][k], At[m][k], acc[ai][bj][m][n], 0, 0, 0); __builtin_amdgcn_s_setprio(0); } while (0)
; #define PG8_WAIT_V(n) asm volatile("s_waitcnt vmcnt(" #n ")" ::: "memory")
; #define PG8_BAR __builtin_amdgcn_s_barrier()
; template <class Epi>
; __device__ __forceinline__ void gemm_phase(LAS unsigned char* lds, const Gemm g, const StaticOrder& S, const Epi& E, int wv) {
;     ...
;             PG8_STAGE(PG8_SB(1, 1), b3 + hstep, voffB);
;             PG8_WAIT_V(6); PG8_BAR; PG8_MMA(1, 1, At, B1); PG8_BAR;
;         }
;     __device__ __forceinline__ void operator()(const f32x4 (&acc)[2][2][4][2], const Unit& u, int wr, int wc, int fr, int fq) const {
;         const float* gate = (u.pm >= 64) ? gate1 : gate0;
;         f32x4 gv[2][2];
; #pragma unroll
;         for (int bj = 0; bj < 2; ++bj)
; #pragma unroll
;             for (int n = 0; n < 2; ++n) gv[bj][n] = *(const f32x4*)(gate + u.pn * 256 + bj * 128 + wc * 32 + n * 16 + 4 * fq);
; #pragma unroll
;         for (int ai = 0; ai < 2; ++ai)
; #pragma unroll
;             for (int m = 0; m < 4; ++m) {
;                 const size_t row = (size_t)u.pm * 256 + ai * 128 + wr * 64 + 4 * fr + m;
; #pragma unroll
;                 for (int bj = 0; bj < 2; ++bj)
; #pragma unroll
;                     for (int n = 0; n < 2; ++n) {
;                         const f32x4 v = gv[bj][n] * acc[ai][bj][m][n];
;                         u32x2 w; w.x = pk2(v[0], v[1]); w.y = pk2(v[2], v[3]);
;                         *(u32x2*)(O + row * D + u.pn * 256 + bj * 128 + wc * 32 + n * 16 + 4 * fq) = w;
;                     }
	s_setprio 1
	v_mfma_f32_16x16x32_bf16 v[60:63], v[128:131], v[168:171], v[60:63]
	v_mfma_f32_16x16x32_bf16 v[56:59], v[136:139], v[168:171], v[56:59]
	v_mfma_f32_16x16x32_bf16 v[48:51], v[128:131], v[176:179], v[48:51]
	v_mfma_f32_16x16x32_bf16 v[40:43], v[136:139], v[176:179], v[40:43]
	v_mfma_f32_16x16x32_bf16 v[32:35], v[128:131], v[184:187], v[32:35]
	v_mfma_f32_16x16x32_bf16 v[24:27], v[136:139], v[184:187], v[24:27]
	v_mfma_f32_16x16x32_bf16 v[16:19], v[128:131], v[192:195], v[16:19]
	v_mfma_f32_16x16x32_bf16 v[8:11], v[136:139], v[192:195], v[8:11]
	v_mfma_f32_16x16x32_bf16 v[60:63], v[132:135], v[172:175], v[60:63]
	v_mfma_f32_16x16x32_bf16 v[56:59], v[140:143], v[172:175], v[56:59]
	v_mfma_f32_16x16x32_bf16 v[48:51], v[132:135], v[180:183], v[48:51]
	v_mfma_f32_16x16x32_bf16 v[40:43], v[140:143], v[180:183], v[40:43]
	v_mfma_f32_16x16x32_bf16 v[32:35], v[132:135], v[188:191], v[32:35]
	v_mfma_f32_16x16x32_bf16 v[24:27], v[140:143], v[188:191], v[24:27]
	v_mfma_f32_16x16x32_bf16 v[16:19], v[132:135], v[196:199], v[16:19]
	v_mfma_f32_16x16x32_bf16 v[8:11], v[140:143], v[196:199], v[8:11]
	v_mfma_f32_16x16x32_bf16 v[52:55], v[200:203], v[168:171], v[52:55]
	v_mfma_f32_16x16x32_bf16 v[44:47], v[208:211], v[168:171], v[44:47]
	v_mfma_f32_16x16x32_bf16 v[36:39], v[200:203], v[176:179], v[36:39]
	v_mfma_f32_16x16x32_bf16 v[28:31], v[208:211], v[176:179], v[28:31]
	v_mfma_f32_16x16x32_bf16 v[20:23], v[200:203], v[184:187], v[20:23]
	v_mfma_f32_16x16x32_bf16 v[12:15], v[208:211], v[184:187], v[12:15]
	v_mfma_f32_16x16x32_bf16 v[4:7], v[200:203], v[192:195], v[4:7]
	v_mfma_f32_16x16x32_bf16 v[0:3], v[208:211], v[192:195], v[0:3]
	v_mfma_f32_16x16x32_bf16 v[52:55], v[204:207], v[172:175], v[52:55]
	v_mfma_f32_16x16x32_bf16 v[44:47], v[212:215], v[172:175], v[44:47]
	v_mfma_f32_16x16x32_bf16 v[36:39], v[204:207], v[180:183], v[36:39]
	v_mfma_f32_16x16x32_bf16 v[28:31], v[212:215], v[180:183], v[28:31]
	v_mfma_f32_16x16x32_bf16 v[20:23], v[204:207], v[188:191], v[20:23]
	v_mfma_f32_16x16x32_bf16 v[12:15], v[212:215], v[188:191], v[12:15]
	v_mfma_f32_16x16x32_bf16 v[4:7], v[204:207], v[196:199], v[4:7]
	v_mfma_f32_16x16x32_bf16 v[0:3], v[212:215], v[196:199], v[0:3]
	s_setprio 0
	s_add_i32 s74, s74, 2
	s_add_u32 s38, s38, 0x100
	s_addc_u32 s39, s39, 0
	s_add_u32 s37, s37, 0x100
	s_addc_u32 s73, s73, 0
	s_cmp_gt_u32 s74, 41
	s_barrier
	s_cbranch_scc0 .LBB0_1122
	s_mov_b32 s37, -1
	s_cmp_gt_i32 s36, 63
	v_mbcnt_lo_u32_b32 v128, s37, 0
	v_mbcnt_hi_u32_b32 v152, s37, v128
	s_cselect_b32 s37, s66, 0x1645000
	s_add_u32 s37, s10, s37
	s_addc_u32 s42, s11, 0
	s_lshl_b32 s38, s12, 8
	s_ashr_i32 s39, s38, 31
	s_lshl_b64 s[40:41], s[38:39], 2
	s_add_u32 s12, s37, s40
	s_addc_u32 s37, s42, s41
	s_lshl_b32 s40, s56, 2
	v_lshrrev_b32_e32 v128, 2, v152
	s_add_u32 s40, s12, s40
	v_and_b32_e32 v162, 28, v128
	s_addc_u32 s41, s37, 0
	v_lshlrev_b32_e32 v128, 2, v162
	s_nop 0
	s_ashr_i32 s37, s36, 31
	s_lshl_b64 s[36:37], s[36:37], 8
	s_add_u32 s12, s36, s55
	v_lshlrev_b32_e32 v163, 2, v152
	s_addc_u32 s36, s37, s59
	v_bfe_u32 v222, v152, 5, 1
	v_bfe_u32 v152, v152, 4, 1
	v_lshlrev_b32_e32 v222, 4, v222
	v_lshl_or_b32 v152, v152, 5, v222
	v_and_or_b32 v162, v163, 60, s12
	v_mov_b32_e32 v163, s36
	v_lshlrev_b64 v[162:163], 11, v[162:163]
	v_lshl_add_u64 v[162:163], s[14:15], 0, v[162:163]
	s_lshl_b32 s12, s56, 1
	v_lshl_add_u64 v[162:163], s[38:39], 1, v[162:163]
	v_lshl_add_u64 v[162:163], v[162:163], 0, s[12:13]
	v_lshl_add_u64 v[162:163], v[162:163], 0, v[152:153]
	v_lshl_add_u64 v[168:169], v[162:163], 0, s[18:19]
	v_lshl_add_u64 v[170:171], v[162:163], 0, s[22:23]
	s_mov_b32 s12, s71
	s_nop 0
	v_lshl_add_u64 v[222:223], v[162:163], 0, s[30:31]
	s_mov_b32 s36, s72
	s_mov_b64 s[40:41], s[6:7]
	s_mov_b64 s[38:39], s[4:5]
	v_pk_mul_f32 v[124:125], v[124:125], v[236:237]
	v_pk_mul_f32 v[126:127], v[126:127], v[238:239]
	v_pk_mul_f32 v[120:121], v[120:121], v[232:233]
	v_pk_mul_f32 v[122:123], v[122:123], v[234:235]
	v_cvt_pk_bf16_f32 v124, v124, v125
	v_cvt_pk_bf16_f32 v125, v126, v127
	v_cvt_pk_bf16_f32 v126, v120, v121
	v_cvt_pk_bf16_f32 v127, v122, v123
	v_pk_mul_f32 v[104:105], v[104:105], v[228:229]
	v_pk_mul_f32 v[106:107], v[106:107], v[230:231]
	v_pk_mul_f32 v[100:101], v[100:101], v[224:225]
	v_pk_mul_f32 v[102:103], v[102:103], v[226:227]
	v_permlane16_swap_b32_e32 v124, v126
	v_permlane16_swap_b32_e32 v125, v127
	global_store_dwordx4 v[162:163], v[124:127], off
	v_cvt_pk_bf16_f32 v104, v104, v105
	v_cvt_pk_bf16_f32 v105, v106, v107
	v_cvt_pk_bf16_f32 v106, v100, v101
	v_cvt_pk_bf16_f32 v107, v102, v103
	v_pk_mul_f32 v[116:117], v[116:117], v[236:237]
	v_pk_mul_f32 v[118:119], v[118:119], v[238:239]
	v_pk_mul_f32 v[112:113], v[112:113], v[232:233]
	v_pk_mul_f32 v[114:115], v[114:115], v[234:235]
	v_permlane16_swap_b32_e32 v104, v106
	v_permlane16_swap_b32_e32 v105, v107
	global_store_dwordx4 v[162:163], v[104:107], off offset:256
	v_cvt_pk_bf16_f32 v116, v116, v117
	v_cvt_pk_bf16_f32 v117, v118, v119
	v_cvt_pk_bf16_f32 v118, v112, v113
	v_cvt_pk_bf16_f32 v119, v114, v115
	v_pk_mul_f32 v[92:93], v[92:93], v[228:229]
	v_pk_mul_f32 v[94:95], v[94:95], v[230:231]
	v_pk_mul_f32 v[88:89], v[88:89], v[224:225]
	v_pk_mul_f32 v[90:91], v[90:91], v[226:227]
	v_permlane16_swap_b32_e32 v116, v118
	v_permlane16_swap_b32_e32 v117, v119
	global_store_dwordx4 v[162:163], v[116:119], off offset:2048
	v_cvt_pk_bf16_f32 v92, v92, v93
	v_cvt_pk_bf16_f32 v93, v94, v95
	v_cvt_pk_bf16_f32 v94, v88, v89
	v_cvt_pk_bf16_f32 v95, v90, v91
	v_pk_mul_f32 v[108:109], v[108:109], v[236:237]
; __device__ __forceinline__ unsigned pk2(float lo, float hi) { unsigned r; asm("v_cvt_pk_bf16_f32 %0, %1, %2" : "=v"(r) : "v"(lo), "v"(hi)); return r; }
; #define PG8_WAIT_V(n) asm volatile("s_waitcnt vmcnt(" #n ")" ::: "memory")
; #define PG8_BAR __builtin_amdgcn_s_barrier()
; template <class Epi>
; __device__ __forceinline__ void gemm_phase(LAS unsigned char* lds, const Gemm g, const StaticOrder& S, const Epi& E, int wv) {
;     ...
;         if (!has_next) break;
; #pragma unroll
;         for (int a = 0; a < 2; ++a)
; #pragma unroll
;             for (int b = 0; b < 2; ++b)
; #pragma unroll
;                 for (int m = 0; m < 4; ++m)
; #pragma unroll
;                     for (int n = 0; n < 2; ++n) acc[a][b][m][n] = (f32x4){0.f, 0.f, 0.f, 0.f};
;         cur = nxt; cA = nA; cB = nB; ++ui;
;     }
;     PG8_WAIT_V(0);
;     if (wr == 0) PG8_BAR;
;     PG8_BAR;
;     __device__ __forceinline__ void operator()(const f32x4 (&acc)[2][2][4][2], const Unit& u, int wr, int wc, int fr, int fq) const {
;     ...
;         for (int ai = 0; ai < 2; ++ai)
; #pragma unroll
;             for (int m = 0; m < 4; ++m) {
;                 const size_t row = (size_t)u.pm * 256 + ai * 128 + wr * 64 + 4 * fr + m;
; #pragma unroll
;                 for (int bj = 0; bj < 2; ++bj)
; #pragma unroll
;                     for (int n = 0; n < 2; ++n) {
;                         const f32x4 v = gv[bj][n] * acc[ai][bj][m][n];
;                         u32x2 w; w.x = pk2(v[0], v[1]); w.y = pk2(v[2], v[3]);
;                         *(u32x2*)(O + row * D + u.pn * 256 + bj * 128 + wc * 32 + n * 16 + 4 * fq) = w;
;                     }
	v_pk_mul_f32 v[110:111], v[110:111], v[238:239]
	v_pk_mul_f32 v[96:97], v[96:97], v[232:233]
	v_pk_mul_f32 v[98:99], v[98:99], v[234:235]
	v_permlane16_swap_b32_e32 v92, v94
	v_permlane16_swap_b32_e32 v93, v95
	global_store_dwordx4 v[162:163], v[92:95], off offset:2304
	v_cvt_pk_bf16_f32 v108, v108, v109
	v_cvt_pk_bf16_f32 v109, v110, v111
	v_cvt_pk_bf16_f32 v110, v96, v97
	v_cvt_pk_bf16_f32 v111, v98, v99
	v_pk_mul_f32 v[84:85], v[84:85], v[228:229]
	v_pk_mul_f32 v[86:87], v[86:87], v[230:231]
	v_pk_mul_f32 v[76:77], v[76:77], v[224:225]
	v_pk_mul_f32 v[78:79], v[78:79], v[226:227]
	v_permlane16_swap_b32_e32 v108, v110
	v_permlane16_swap_b32_e32 v109, v111
	global_store_dwordx4 v[168:169], v[108:111], off
	v_cvt_pk_bf16_f32 v84, v84, v85
	v_cvt_pk_bf16_f32 v85, v86, v87
	v_cvt_pk_bf16_f32 v86, v76, v77
	v_cvt_pk_bf16_f32 v87, v78, v79
	v_pk_mul_f32 v[80:81], v[80:81], v[236:237]
	v_pk_mul_f32 v[82:83], v[82:83], v[238:239]
	v_pk_mul_f32 v[72:73], v[72:73], v[232:233]
	v_pk_mul_f32 v[74:75], v[74:75], v[234:235]
	v_permlane16_swap_b32_e32 v84, v86
	v_permlane16_swap_b32_e32 v85, v87
	global_store_dwordx4 v[168:169], v[84:87], off offset:256
	v_cvt_pk_bf16_f32 v80, v80, v81
	v_cvt_pk_bf16_f32 v81, v82, v83
	v_cvt_pk_bf16_f32 v82, v72, v73
	v_cvt_pk_bf16_f32 v83, v74, v75
	v_pk_mul_f32 v[68:69], v[68:69], v[228:229]
	v_pk_mul_f32 v[70:71], v[70:71], v[230:231]
	v_pk_mul_f32 v[64:65], v[64:65], v[224:225]
	v_pk_mul_f32 v[66:67], v[66:67], v[226:227]
	v_permlane16_swap_b32_e32 v80, v82
	v_permlane16_swap_b32_e32 v81, v83
	global_store_dwordx4 v[168:169], v[80:83], off offset:2048
	v_cvt_pk_bf16_f32 v68, v68, v69
	v_cvt_pk_bf16_f32 v69, v70, v71
	v_cvt_pk_bf16_f32 v70, v64, v65
	v_cvt_pk_bf16_f32 v71, v66, v67
	v_pk_mul_f32 v[60:61], v[60:61], v[236:237]
	v_pk_mul_f32 v[62:63], v[62:63], v[238:239]
	v_pk_mul_f32 v[56:57], v[56:57], v[232:233]
	v_pk_mul_f32 v[58:59], v[58:59], v[234:235]
	v_permlane16_swap_b32_e32 v68, v70
	v_permlane16_swap_b32_e32 v69, v71
	global_store_dwordx4 v[168:169], v[68:71], off offset:2304
	v_cvt_pk_bf16_f32 v60, v60, v61
	v_cvt_pk_bf16_f32 v61, v62, v63
	v_cvt_pk_bf16_f32 v62, v56, v57
	v_cvt_pk_bf16_f32 v63, v58, v59
	v_pk_mul_f32 v[52:53], v[52:53], v[228:229]
	v_pk_mul_f32 v[54:55], v[54:55], v[230:231]
	v_pk_mul_f32 v[44:45], v[44:45], v[224:225]
	v_pk_mul_f32 v[46:47], v[46:47], v[226:227]
	v_permlane16_swap_b32_e32 v60, v62
	v_permlane16_swap_b32_e32 v61, v63
	global_store_dwordx4 v[170:171], v[60:63], off
	v_cvt_pk_bf16_f32 v52, v52, v53
	v_cvt_pk_bf16_f32 v53, v54, v55
	v_cvt_pk_bf16_f32 v54, v44, v45
	v_cvt_pk_bf16_f32 v55, v46, v47
	v_pk_mul_f32 v[48:49], v[48:49], v[236:237]
	v_pk_mul_f32 v[50:51], v[50:51], v[238:239]
	v_pk_mul_f32 v[40:41], v[40:41], v[232:233]
	v_pk_mul_f32 v[42:43], v[42:43], v[234:235]
	v_permlane16_swap_b32_e32 v52, v54
	v_permlane16_swap_b32_e32 v53, v55
	global_store_dwordx4 v[170:171], v[52:55], off offset:256
	v_cvt_pk_bf16_f32 v48, v48, v49
	v_cvt_pk_bf16_f32 v49, v50, v51
	v_cvt_pk_bf16_f32 v50, v40, v41
	v_cvt_pk_bf16_f32 v51, v42, v43
	v_pk_mul_f32 v[36:37], v[36:37], v[228:229]
	v_pk_mul_f32 v[38:39], v[38:39], v[230:231]
	v_pk_mul_f32 v[28:29], v[28:29], v[224:225]
	v_pk_mul_f32 v[30:31], v[30:31], v[226:227]
	v_permlane16_swap_b32_e32 v48, v50
	v_permlane16_swap_b32_e32 v49, v51
	global_store_dwordx4 v[170:171], v[48:51], off offset:2048
	v_cvt_pk_bf16_f32 v36, v36, v37
	v_cvt_pk_bf16_f32 v37, v38, v39
	v_cvt_pk_bf16_f32 v38, v28, v29
	v_cvt_pk_bf16_f32 v39, v30, v31
	v_pk_mul_f32 v[32:33], v[32:33], v[236:237]
	v_pk_mul_f32 v[34:35], v[34:35], v[238:239]
	v_pk_mul_f32 v[24:25], v[24:25], v[232:233]
	v_pk_mul_f32 v[26:27], v[26:27], v[234:235]
	v_permlane16_swap_b32_e32 v36, v38
	v_permlane16_swap_b32_e32 v37, v39
	global_store_dwordx4 v[170:171], v[36:39], off offset:2304
	v_cvt_pk_bf16_f32 v32, v32, v33
	v_cvt_pk_bf16_f32 v33, v34, v35
	v_cvt_pk_bf16_f32 v34, v24, v25
	v_cvt_pk_bf16_f32 v35, v26, v27
	v_pk_mul_f32 v[20:21], v[20:21], v[228:229]
	v_pk_mul_f32 v[22:23], v[22:23], v[230:231]
	v_pk_mul_f32 v[12:13], v[12:13], v[224:225]
	v_pk_mul_f32 v[14:15], v[14:15], v[226:227]
	v_permlane16_swap_b32_e32 v32, v34
	v_permlane16_swap_b32_e32 v33, v35
	global_store_dwordx4 v[222:223], v[32:35], off
	v_cvt_pk_bf16_f32 v20, v20, v21
	v_cvt_pk_bf16_f32 v21, v22, v23
	v_cvt_pk_bf16_f32 v22, v12, v13
	v_cvt_pk_bf16_f32 v23, v14, v15
	v_pk_mul_f32 v[16:17], v[16:17], v[236:237]
	v_pk_mul_f32 v[18:19], v[18:19], v[238:239]
	v_pk_mul_f32 v[8:9], v[8:9], v[232:233]
	v_pk_mul_f32 v[10:11], v[10:11], v[234:235]
	v_permlane16_swap_b32_e32 v20, v22
	v_permlane16_swap_b32_e32 v21, v23
	global_store_dwordx4 v[222:223], v[20:23], off offset:256
	v_cvt_pk_bf16_f32 v16, v16, v17
	v_cvt_pk_bf16_f32 v17, v18, v19
	v_cvt_pk_bf16_f32 v18, v8, v9
	v_cvt_pk_bf16_f32 v19, v10, v11
	v_pk_mul_f32 v[4:5], v[4:5], v[228:229]
	v_pk_mul_f32 v[6:7], v[6:7], v[230:231]
	v_pk_mul_f32 v[0:1], v[0:1], v[224:225]
	v_pk_mul_f32 v[2:3], v[2:3], v[226:227]
	v_permlane16_swap_b32_e32 v16, v18
	v_permlane16_swap_b32_e32 v17, v19
	global_store_dwordx4 v[222:223], v[16:19], off offset:2048
	v_cvt_pk_bf16_f32 v4, v4, v5
	v_cvt_pk_bf16_f32 v5, v6, v7
	v_cvt_pk_bf16_f32 v6, v0, v1
	v_cvt_pk_bf16_f32 v7, v2, v3
	s_nop 1
	v_permlane16_swap_b32_e32 v4, v6
	v_permlane16_swap_b32_e32 v5, v7
	global_store_dwordx4 v[222:223], v[4:7], off offset:2304
	s_and_b64 vcc, exec, s[8:9]
	s_cbranch_vccz .LBB0_1111
	s_waitcnt vmcnt(0)
	s_cmpk_gt_u32 s44, 0xff
	s_cbranch_scc1 .LBB0_1126
	s_barrier

; #define LAS __attribute__((address_space(3)))
; __global__ void __launch_bounds__(512, 2) fwd_megakernel(Params p_arg) {
;     extern __shared__ __attribute__((aligned(16))) unsigned char shm[];
;     cg::grid_group grid = cg::this_grid();
;     LAS unsigned char* lds = (LAS unsigned char*)shm;
;     pg8::StaticOrder so;
;     const int wv = __builtin_amdgcn_readfirstlane((int)(threadIdx.x >> 6));
	.amdhsa_kernel _Z14fwd_megakernel6Params
		.amdhsa_group_segment_fixed_size 0
		.amdhsa_private_segment_fixed_size 0
		.amdhsa_kernarg_size 472
		.amdhsa_user_sgpr_count 2
		.amdhsa_user_sgpr_dispatch_ptr 0
		.amdhsa_user_sgpr_queue_ptr 0
		.amdhsa_user_sgpr_kernarg_segment_ptr 1
		.amdhsa_user_sgpr_dispatch_id 0
		.amdhsa_user_sgpr_kernarg_preload_length 0
		.amdhsa_user_sgpr_kernarg_preload_offset 0
		.amdhsa_user_sgpr_private_segment_size 0
		.amdhsa_uses_dynamic_stack 0
		.amdhsa_enable_private_segment 0
		.amdhsa_system_sgpr_workgroup_id_x 1
		.amdhsa_system_sgpr_workgroup_id_y 0
		.amdhsa_system_sgpr_workgroup_id_z 0
		.amdhsa_system_sgpr_workgroup_info 0
		.amdhsa_system_vgpr_workitem_id 2
		.amdhsa_next_free_vgpr 256
		.amdhsa_next_free_sgpr 102
		.amdhsa_accum_offset 256
		.amdhsa_reserve_vcc 1
		.amdhsa_float_round_mode_32 0
		.amdhsa_float_round_mode_16_64 0
		.amdhsa_float_denorm_mode_32 3
		.amdhsa_float_denorm_mode_16_64 3
		.amdhsa_dx10_clamp 1
		.amdhsa_ieee_mode 1
		.amdhsa_fp16_overflow 0
		.amdhsa_tg_split 0
		.amdhsa_exception_fp_ieee_invalid_op 0
		.amdhsa_exception_fp_denorm_src 0
		.amdhsa_exception_fp_ieee_div_zero 0
		.amdhsa_exception_fp_ieee_overflow 0
		.amdhsa_exception_fp_ieee_underflow 0
		.amdhsa_exception_fp_ieee_inexact 0
		.amdhsa_exception_int_div_zero 0
	.end_amdhsa_kernel

; #define LAS __attribute__((address_space(3)))
; __global__ void __launch_bounds__(512, 2) fwd_megakernel(Params p_arg) {
;     extern __shared__ __attribute__((aligned(16))) unsigned char shm[];
;     cg::grid_group grid = cg::this_grid();
;     LAS unsigned char* lds = (LAS unsigned char*)shm;
;     pg8::StaticOrder so;
;     const int wv = __builtin_amdgcn_readfirstlane((int)(threadIdx.x >> 6));
amdhsa.kernels:
  - .agpr_count:     0
    .args:
      - .offset:         0
        .size:           216
        .value_kind:     by_value
      - .offset:         216
        .size:           4
        .value_kind:     hidden_block_count_x
      - .offset:         220
        .size:           4
        .value_kind:     hidden_block_count_y
      - .offset:         224
        .size:           4
        .value_kind:     hidden_block_count_z
      - .offset:         228
        .size:           2
        .value_kind:     hidden_group_size_x
      - .offset:         230
        .size:           2
        .value_kind:     hidden_group_size_y
      - .offset:         232
        .size:           2
        .value_kind:     hidden_group_size_z
      - .offset:         234
        .size:           2
        .value_kind:     hidden_remainder_x
      - .offset:         236
        .size:           2
        .value_kind:     hidden_remainder_y
      - .offset:         238
        .size:           2
        .value_kind:     hidden_remainder_z
      - .offset:         256
        .size:           8
        .value_kind:     hidden_global_offset_x
      - .offset:         264
        .size:           8
        .value_kind:     hidden_global_offset_y
      - .offset:         272
        .size:           8
        .value_kind:     hidden_global_offset_z
      - .offset:         280
        .size:           2
        .value_kind:     hidden_grid_dims
      - .offset:         304
        .size:           8
        .value_kind:     hidden_multigrid_sync_arg
      - .offset:         336
        .size:           4
        .value_kind:     hidden_dynamic_lds_size
    .group_segment_fixed_size: 0
    .kernarg_segment_align: 8
    .kernarg_segment_size: 472
    .language:       OpenCL C
    .language_version:
      - 2
      - 0
    .max_flat_workgroup_size: 512
    .name:           _Z14fwd_megakernel6Params
    .private_segment_fixed_size: 0
    .sgpr_count:     108
    .sgpr_spill_count: 0
    .symbol:         _Z14fwd_megakernel6Params.kd
    .uniform_work_group_size: 1
    .uses_dynamic_stack: false
    .vgpr_count:     256
    .vgpr_spill_count: 0
    .wavefront_size: 64
